# HGRN prep waves: z/q rows loaded straight into registers two chunks ahead (lane = step), V image ring of four LDS slots fetched two chunks ahead; MFMA f32 fold
# baseline (speedup 1.0000x reference)
.Lh2_prep:
	v_and_b32_e32 v244, 63, v200
	v_lshrrev_b32_e32 v243, 4, v244
	s_lshl_b32 s1, s8, 12
	s_add_u32 s13, s1, 0xfff
	s_cmp_eq_u32 s12, 0
	s_cselect_b64 s[18:19], -1, 0
	v_mov_b32_e32 v242, 0x1c00
	v_add_u32_e32 v239, s1, v244
	v_sub_u32_e32 v240, s13, v244
	v_cndmask_b32_e64 v239, v240, v239, s[18:19]
	v_mul_lo_u32 v228, v239, v242
	s_lshl_b32 s17, s0, 4
	v_add_u32_e32 v240, 0, v243
	v_add_u32_e32 v240, s17, v240
	v_add_u32_e32 v239, s1, v240
	v_sub_u32_e32 v240, s13, v240
	v_cndmask_b32_e64 v239, v240, v239, s[18:19]
	v_mul_lo_u32 v239, v239, v242
	v_lshl_or_b32 v240, v243, 2, 0
	v_and_b32_e32 v238, 15, v244
	v_xor_b32_e32 v240, v240, v238
	v_lshl_add_u32 v252, v240, 4, v239
	v_add_u32_e32 v240, 4, v243
	v_add_u32_e32 v240, s17, v240
	v_add_u32_e32 v239, s1, v240
	v_sub_u32_e32 v240, s13, v240
	v_cndmask_b32_e64 v239, v240, v239, s[18:19]
	v_mul_lo_u32 v239, v239, v242
	v_lshl_or_b32 v240, v243, 2, 1
	v_and_b32_e32 v238, 15, v244
	v_xor_b32_e32 v240, v240, v238
	v_lshl_add_u32 v253, v240, 4, v239
	v_add_u32_e32 v240, 8, v243
	v_add_u32_e32 v240, s17, v240
	v_add_u32_e32 v239, s1, v240
	v_sub_u32_e32 v240, s13, v240
	v_cndmask_b32_e64 v239, v240, v239, s[18:19]
	v_mul_lo_u32 v239, v239, v242
	v_lshl_or_b32 v240, v243, 2, 2
	v_and_b32_e32 v238, 15, v244
	v_xor_b32_e32 v240, v240, v238
	v_lshl_add_u32 v254, v240, 4, v239
	v_add_u32_e32 v240, 12, v243
	v_add_u32_e32 v240, s17, v240
	v_add_u32_e32 v239, s1, v240
	v_sub_u32_e32 v240, s13, v240
	v_cndmask_b32_e64 v239, v240, v239, s[18:19]
	v_mul_lo_u32 v239, v239, v242
	v_lshl_or_b32 v240, v243, 2, 3
	v_and_b32_e32 v238, 15, v244
	v_xor_b32_e32 v240, v240, v238
	v_lshl_add_u32 v255, v240, 4, v239
	s_mov_b32 s33, 0x70000
	s_sub_u32 s13, 0, s33
	s_cmp_eq_u32 s12, 0
	s_cselect_b32 s33, s33, s13
	s_lshl_b32 s13, s9, 8
	s_add_u32 s34, s92, s13
	s_addc_u32 s35, s93, 0
	s_lshl_b32 s1, s0, 6
	s_add_u32 s30, s34, s1
	s_addc_u32 s31, s35, 0
	s_add_u32 s34, s34, 0xc00
	s_addc_u32 s35, s35, 0
	s_movk_i32 s1, 0x800
	s_cmp_eq_u32 s12, 0
	s_cselect_b32 s1, 0x400, s1
	s_add_u32 s14, s30, s1
	s_addc_u32 s15, s31, 0
	v_and_b32_e32 v241, 3, v244
	v_xor_b32_e32 v241, s0, v241
	v_lshlrev_b32_e32 v241, 6, v241
	v_lshl_add_u32 v241, v244, 8, v241
	v_bfe_u32 v240, v244, 2, 2
	v_xor_b32_e32 v239, 0, v240
	v_lshl_add_u32 v222, v239, 4, v241
	v_xor_b32_e32 v239, 1, v240
	v_lshl_add_u32 v223, v239, 4, v241
	v_xor_b32_e32 v239, 2, v240
	v_lshl_add_u32 v224, v239, 4, v241
	v_xor_b32_e32 v239, 3, v240
	v_lshl_add_u32 v225, v239, 4, v241
	v_mov_b32_e32 v239, 0x110
	v_mul_lo_u32 v241, v244, v239
	s_lshl_b32 s1, s0, 6
	v_add_u32_e32 v241, s1, v241
	v_add_u32_e32 v226, 0x10400, v241
	v_add_u32_e32 v227, 0x14800, v241
	s_lshl_b32 s1, s0, 7
	v_mov_b32_e32 v247, s1
	s_lshl_b32 s72, s0, 12
	global_load_dwordx4 v[16:19], v228, s[14:15]
	global_load_dwordx4 v[20:23], v228, s[14:15] offset:16
	global_load_dwordx4 v[24:27], v228, s[14:15] offset:32
	global_load_dwordx4 v[28:31], v228, s[14:15] offset:48
	s_add_u32 s1, s72, 0x8400
	s_add_u32 m0, s1, 0
	s_nop 0
	global_load_lds_dwordx4 v252, s[34:35]
	s_add_u32 m0, s1, 1024
	s_nop 0
	global_load_lds_dwordx4 v253, s[34:35]
	s_add_u32 m0, s1, 2048
	s_nop 0
	global_load_lds_dwordx4 v254, s[34:35]
	s_add_u32 m0, s1, 3072
	s_nop 0
	global_load_lds_dwordx4 v255, s[34:35]
	global_load_dwordx4 v[0:3], v228, s[30:31]
	global_load_dwordx4 v[4:7], v228, s[30:31] offset:16
	global_load_dwordx4 v[8:11], v228, s[30:31] offset:32
	global_load_dwordx4 v[12:15], v228, s[30:31] offset:48
	v_add_u32_e32 v252, s33, v252
	v_add_u32_e32 v253, s33, v253
	v_add_u32_e32 v254, s33, v254
	v_add_u32_e32 v255, s33, v255
	v_add_u32_e32 v228, s33, v228
	global_load_dwordx4 v[32:35], v228, s[14:15]
	global_load_dwordx4 v[36:39], v228, s[14:15] offset:16
	global_load_dwordx4 v[40:43], v228, s[14:15] offset:32
	global_load_dwordx4 v[44:47], v228, s[14:15] offset:48
	s_add_u32 s1, s72, 0xc400
	s_add_u32 m0, s1, 0
	s_nop 0
	global_load_lds_dwordx4 v252, s[34:35]
	s_add_u32 m0, s1, 1024
	s_nop 0
	global_load_lds_dwordx4 v253, s[34:35]
	s_add_u32 m0, s1, 2048
	s_nop 0
	global_load_lds_dwordx4 v254, s[34:35]
	s_add_u32 m0, s1, 3072
	s_nop 0
	global_load_lds_dwordx4 v255, s[34:35]
	global_load_dwordx4 v[48:51], v228, s[30:31]
	global_load_dwordx4 v[52:55], v228, s[30:31] offset:16
	global_load_dwordx4 v[56:59], v228, s[30:31] offset:32
	global_load_dwordx4 v[60:63], v228, s[30:31] offset:48
	v_add_u32_e32 v252, s33, v252
	v_add_u32_e32 v253, s33, v253
	v_add_u32_e32 v254, s33, v254
	v_add_u32_e32 v255, s33, v255
	v_add_u32_e32 v228, s33, v228
	s_mov_b32 s77, 0x1b400
	s_mov_b32 s70, 0
.Lh2_prep_loop:
	s_waitcnt vmcnt(12)
	s_cmp_ge_u32 s70, 31
	s_cselect_b32 s76, 0, s33
	s_add_u32 s1, s72, s77
	s_add_u32 s77, s77, 0x4000
	s_cmp_eq_u32 s77, 0x10400
	s_cselect_b32 s77, 0x1b400, s77
	s_cmp_eq_u32 s77, 0x23400
	s_cselect_b32 s77, 0x8400, s77
	v_lshlrev_b32_e32 v96, 16, v16
	v_and_b32_e32 v97, 0xffff0000, v16
	v_lshlrev_b32_e32 v98, 16, v17
	v_and_b32_e32 v99, 0xffff0000, v17
	v_lshlrev_b32_e32 v100, 16, v18
	v_and_b32_e32 v101, 0xffff0000, v18
	v_lshlrev_b32_e32 v102, 16, v19
	v_and_b32_e32 v103, 0xffff0000, v19
	v_lshlrev_b32_e32 v104, 16, v20
	v_and_b32_e32 v105, 0xffff0000, v20
	v_lshlrev_b32_e32 v106, 16, v21
	v_and_b32_e32 v107, 0xffff0000, v21
	v_lshlrev_b32_e32 v108, 16, v22
	v_and_b32_e32 v109, 0xffff0000, v22
	v_lshlrev_b32_e32 v110, 16, v23
	v_and_b32_e32 v111, 0xffff0000, v23
	v_lshlrev_b32_e32 v112, 16, v24
	v_and_b32_e32 v113, 0xffff0000, v24
	v_lshlrev_b32_e32 v114, 16, v25
	v_and_b32_e32 v115, 0xffff0000, v25
	v_lshlrev_b32_e32 v116, 16, v26
	v_and_b32_e32 v117, 0xffff0000, v26
	v_lshlrev_b32_e32 v118, 16, v27
	v_and_b32_e32 v119, 0xffff0000, v27
	v_lshlrev_b32_e32 v120, 16, v28
	v_and_b32_e32 v121, 0xffff0000, v28
	v_lshlrev_b32_e32 v122, 16, v29
	v_and_b32_e32 v123, 0xffff0000, v29
	v_lshlrev_b32_e32 v124, 16, v30
	v_and_b32_e32 v125, 0xffff0000, v30
	v_lshlrev_b32_e32 v126, 16, v31
	v_and_b32_e32 v127, 0xffff0000, v31
	v_sub_f32_e32 v128, 1.0, v96
	v_sub_f32_e32 v129, 1.0, v97
	v_sub_f32_e32 v130, 1.0, v98
	v_sub_f32_e32 v131, 1.0, v99
	v_sub_f32_e32 v132, 1.0, v100
	v_sub_f32_e32 v133, 1.0, v101
	v_sub_f32_e32 v134, 1.0, v102
	v_sub_f32_e32 v135, 1.0, v103
	global_load_dwordx4 v[16:19], v228, s[14:15]
	v_sub_f32_e32 v136, 1.0, v104
	v_sub_f32_e32 v137, 1.0, v105
	v_sub_f32_e32 v138, 1.0, v106
	v_sub_f32_e32 v139, 1.0, v107
	v_sub_f32_e32 v140, 1.0, v108
	v_sub_f32_e32 v141, 1.0, v109
	v_sub_f32_e32 v142, 1.0, v110
	v_sub_f32_e32 v143, 1.0, v111
	v_sub_f32_e32 v144, 1.0, v112
	v_sub_f32_e32 v145, 1.0, v113
	v_sub_f32_e32 v146, 1.0, v114
	v_sub_f32_e32 v147, 1.0, v115
	v_sub_f32_e32 v148, 1.0, v116
	v_sub_f32_e32 v149, 1.0, v117
	v_sub_f32_e32 v150, 1.0, v118
	v_sub_f32_e32 v151, 1.0, v119
	v_sub_f32_e32 v152, 1.0, v120
	v_sub_f32_e32 v153, 1.0, v121
	v_sub_f32_e32 v154, 1.0, v122
	v_sub_f32_e32 v155, 1.0, v123
	v_sub_f32_e32 v156, 1.0, v124
	v_sub_f32_e32 v157, 1.0, v125
	v_sub_f32_e32 v158, 1.0, v126
	v_sub_f32_e32 v159, 1.0, v127
	global_load_dwordx4 v[20:23], v228, s[14:15] offset:16
	v_mul_f32_dpp v128, v128, v128 row_shr:1 row_mask:0xf bank_mask:0xf
	v_mul_f32_dpp v129, v129, v129 row_shr:1 row_mask:0xf bank_mask:0xf
	v_mul_f32_dpp v130, v130, v130 row_shr:1 row_mask:0xf bank_mask:0xf
	v_mul_f32_dpp v131, v131, v131 row_shr:1 row_mask:0xf bank_mask:0xf
	v_mul_f32_dpp v132, v132, v132 row_shr:1 row_mask:0xf bank_mask:0xf
	v_mul_f32_dpp v133, v133, v133 row_shr:1 row_mask:0xf bank_mask:0xf
	v_mul_f32_dpp v134, v134, v134 row_shr:1 row_mask:0xf bank_mask:0xf
	v_mul_f32_dpp v135, v135, v135 row_shr:1 row_mask:0xf bank_mask:0xf
	v_mul_f32_dpp v136, v136, v136 row_shr:1 row_mask:0xf bank_mask:0xf
	v_mul_f32_dpp v137, v137, v137 row_shr:1 row_mask:0xf bank_mask:0xf
	v_mul_f32_dpp v138, v138, v138 row_shr:1 row_mask:0xf bank_mask:0xf
	v_mul_f32_dpp v139, v139, v139 row_shr:1 row_mask:0xf bank_mask:0xf
	v_mul_f32_dpp v140, v140, v140 row_shr:1 row_mask:0xf bank_mask:0xf
	v_mul_f32_dpp v141, v141, v141 row_shr:1 row_mask:0xf bank_mask:0xf
	v_mul_f32_dpp v142, v142, v142 row_shr:1 row_mask:0xf bank_mask:0xf
	v_mul_f32_dpp v143, v143, v143 row_shr:1 row_mask:0xf bank_mask:0xf
	v_mul_f32_dpp v144, v144, v144 row_shr:1 row_mask:0xf bank_mask:0xf
	v_mul_f32_dpp v145, v145, v145 row_shr:1 row_mask:0xf bank_mask:0xf
	v_mul_f32_dpp v146, v146, v146 row_shr:1 row_mask:0xf bank_mask:0xf
	v_mul_f32_dpp v147, v147, v147 row_shr:1 row_mask:0xf bank_mask:0xf
	v_mul_f32_dpp v148, v148, v148 row_shr:1 row_mask:0xf bank_mask:0xf
	v_mul_f32_dpp v149, v149, v149 row_shr:1 row_mask:0xf bank_mask:0xf
	v_mul_f32_dpp v150, v150, v150 row_shr:1 row_mask:0xf bank_mask:0xf
	v_mul_f32_dpp v151, v151, v151 row_shr:1 row_mask:0xf bank_mask:0xf
	global_load_dwordx4 v[24:27], v228, s[14:15] offset:32
	v_mul_f32_dpp v152, v152, v152 row_shr:1 row_mask:0xf bank_mask:0xf
	v_mul_f32_dpp v153, v153, v153 row_shr:1 row_mask:0xf bank_mask:0xf
	v_mul_f32_dpp v154, v154, v154 row_shr:1 row_mask:0xf bank_mask:0xf
	v_mul_f32_dpp v155, v155, v155 row_shr:1 row_mask:0xf bank_mask:0xf
	v_mul_f32_dpp v156, v156, v156 row_shr:1 row_mask:0xf bank_mask:0xf
	v_mul_f32_dpp v157, v157, v157 row_shr:1 row_mask:0xf bank_mask:0xf
	v_mul_f32_dpp v158, v158, v158 row_shr:1 row_mask:0xf bank_mask:0xf
	v_mul_f32_dpp v159, v159, v159 row_shr:1 row_mask:0xf bank_mask:0xf
	v_mul_f32_dpp v128, v128, v128 row_shr:2 row_mask:0xf bank_mask:0xf
	v_mul_f32_dpp v129, v129, v129 row_shr:2 row_mask:0xf bank_mask:0xf
	v_mul_f32_dpp v130, v130, v130 row_shr:2 row_mask:0xf bank_mask:0xf
	v_mul_f32_dpp v131, v131, v131 row_shr:2 row_mask:0xf bank_mask:0xf
	v_mul_f32_dpp v132, v132, v132 row_shr:2 row_mask:0xf bank_mask:0xf
	v_mul_f32_dpp v133, v133, v133 row_shr:2 row_mask:0xf bank_mask:0xf
	v_mul_f32_dpp v134, v134, v134 row_shr:2 row_mask:0xf bank_mask:0xf
	v_mul_f32_dpp v135, v135, v135 row_shr:2 row_mask:0xf bank_mask:0xf
	v_mul_f32_dpp v136, v136, v136 row_shr:2 row_mask:0xf bank_mask:0xf
	v_mul_f32_dpp v137, v137, v137 row_shr:2 row_mask:0xf bank_mask:0xf
	v_mul_f32_dpp v138, v138, v138 row_shr:2 row_mask:0xf bank_mask:0xf
	v_mul_f32_dpp v139, v139, v139 row_shr:2 row_mask:0xf bank_mask:0xf
	v_mul_f32_dpp v140, v140, v140 row_shr:2 row_mask:0xf bank_mask:0xf
	v_mul_f32_dpp v141, v141, v141 row_shr:2 row_mask:0xf bank_mask:0xf
	v_mul_f32_dpp v142, v142, v142 row_shr:2 row_mask:0xf bank_mask:0xf
	v_mul_f32_dpp v143, v143, v143 row_shr:2 row_mask:0xf bank_mask:0xf
	global_load_dwordx4 v[28:31], v228, s[14:15] offset:48
	v_mul_f32_dpp v144, v144, v144 row_shr:2 row_mask:0xf bank_mask:0xf
	v_mul_f32_dpp v145, v145, v145 row_shr:2 row_mask:0xf bank_mask:0xf
	v_mul_f32_dpp v146, v146, v146 row_shr:2 row_mask:0xf bank_mask:0xf
	v_mul_f32_dpp v147, v147, v147 row_shr:2 row_mask:0xf bank_mask:0xf
	v_mul_f32_dpp v148, v148, v148 row_shr:2 row_mask:0xf bank_mask:0xf
	v_mul_f32_dpp v149, v149, v149 row_shr:2 row_mask:0xf bank_mask:0xf
	v_mul_f32_dpp v150, v150, v150 row_shr:2 row_mask:0xf bank_mask:0xf
	v_mul_f32_dpp v151, v151, v151 row_shr:2 row_mask:0xf bank_mask:0xf
	v_mul_f32_dpp v152, v152, v152 row_shr:2 row_mask:0xf bank_mask:0xf
	v_mul_f32_dpp v153, v153, v153 row_shr:2 row_mask:0xf bank_mask:0xf
	v_mul_f32_dpp v154, v154, v154 row_shr:2 row_mask:0xf bank_mask:0xf
	v_mul_f32_dpp v155, v155, v155 row_shr:2 row_mask:0xf bank_mask:0xf
	v_mul_f32_dpp v156, v156, v156 row_shr:2 row_mask:0xf bank_mask:0xf
	v_mul_f32_dpp v157, v157, v157 row_shr:2 row_mask:0xf bank_mask:0xf
	v_mul_f32_dpp v158, v158, v158 row_shr:2 row_mask:0xf bank_mask:0xf
	v_mul_f32_dpp v159, v159, v159 row_shr:2 row_mask:0xf bank_mask:0xf
	v_mul_f32_dpp v128, v128, v128 row_shr:4 row_mask:0xf bank_mask:0xf
	v_mul_f32_dpp v129, v129, v129 row_shr:4 row_mask:0xf bank_mask:0xf
	v_mul_f32_dpp v130, v130, v130 row_shr:4 row_mask:0xf bank_mask:0xf
	v_mul_f32_dpp v131, v131, v131 row_shr:4 row_mask:0xf bank_mask:0xf
	v_mul_f32_dpp v132, v132, v132 row_shr:4 row_mask:0xf bank_mask:0xf
	v_mul_f32_dpp v133, v133, v133 row_shr:4 row_mask:0xf bank_mask:0xf
	v_mul_f32_dpp v134, v134, v134 row_shr:4 row_mask:0xf bank_mask:0xf
	v_mul_f32_dpp v135, v135, v135 row_shr:4 row_mask:0xf bank_mask:0xf
	s_add_u32 m0, s1, 0
	s_nop 0
	global_load_lds_dwordx4 v252, s[34:35]
	v_mul_f32_dpp v136, v136, v136 row_shr:4 row_mask:0xf bank_mask:0xf
	v_mul_f32_dpp v137, v137, v137 row_shr:4 row_mask:0xf bank_mask:0xf
	v_mul_f32_dpp v138, v138, v138 row_shr:4 row_mask:0xf bank_mask:0xf
	v_mul_f32_dpp v139, v139, v139 row_shr:4 row_mask:0xf bank_mask:0xf
	v_mul_f32_dpp v140, v140, v140 row_shr:4 row_mask:0xf bank_mask:0xf
	v_mul_f32_dpp v141, v141, v141 row_shr:4 row_mask:0xf bank_mask:0xf
	v_mul_f32_dpp v142, v142, v142 row_shr:4 row_mask:0xf bank_mask:0xf
	v_mul_f32_dpp v143, v143, v143 row_shr:4 row_mask:0xf bank_mask:0xf
	v_mul_f32_dpp v144, v144, v144 row_shr:4 row_mask:0xf bank_mask:0xf
	v_mul_f32_dpp v145, v145, v145 row_shr:4 row_mask:0xf bank_mask:0xf
	v_mul_f32_dpp v146, v146, v146 row_shr:4 row_mask:0xf bank_mask:0xf
	v_mul_f32_dpp v147, v147, v147 row_shr:4 row_mask:0xf bank_mask:0xf
	v_mul_f32_dpp v148, v148, v148 row_shr:4 row_mask:0xf bank_mask:0xf
	v_mul_f32_dpp v149, v149, v149 row_shr:4 row_mask:0xf bank_mask:0xf
	v_mul_f32_dpp v150, v150, v150 row_shr:4 row_mask:0xf bank_mask:0xf
	v_mul_f32_dpp v151, v151, v151 row_shr:4 row_mask:0xf bank_mask:0xf
	v_mul_f32_dpp v152, v152, v152 row_shr:4 row_mask:0xf bank_mask:0xf
	v_mul_f32_dpp v153, v153, v153 row_shr:4 row_mask:0xf bank_mask:0xf
	v_mul_f32_dpp v154, v154, v154 row_shr:4 row_mask:0xf bank_mask:0xf
	v_mul_f32_dpp v155, v155, v155 row_shr:4 row_mask:0xf bank_mask:0xf
	v_mul_f32_dpp v156, v156, v156 row_shr:4 row_mask:0xf bank_mask:0xf
	v_mul_f32_dpp v157, v157, v157 row_shr:4 row_mask:0xf bank_mask:0xf
	v_mul_f32_dpp v158, v158, v158 row_shr:4 row_mask:0xf bank_mask:0xf
	v_mul_f32_dpp v159, v159, v159 row_shr:4 row_mask:0xf bank_mask:0xf
	s_add_u32 m0, s1, 1024
	s_nop 0
	global_load_lds_dwordx4 v253, s[34:35]
	v_mul_f32_dpp v128, v128, v128 row_shr:8 row_mask:0xf bank_mask:0xf
	v_mul_f32_dpp v129, v129, v129 row_shr:8 row_mask:0xf bank_mask:0xf
	v_mul_f32_dpp v130, v130, v130 row_shr:8 row_mask:0xf bank_mask:0xf
	v_mul_f32_dpp v131, v131, v131 row_shr:8 row_mask:0xf bank_mask:0xf
	v_mul_f32_dpp v132, v132, v132 row_shr:8 row_mask:0xf bank_mask:0xf
	v_mul_f32_dpp v133, v133, v133 row_shr:8 row_mask:0xf bank_mask:0xf
	v_mul_f32_dpp v134, v134, v134 row_shr:8 row_mask:0xf bank_mask:0xf
	v_mul_f32_dpp v135, v135, v135 row_shr:8 row_mask:0xf bank_mask:0xf
	v_mul_f32_dpp v136, v136, v136 row_shr:8 row_mask:0xf bank_mask:0xf
	v_mul_f32_dpp v137, v137, v137 row_shr:8 row_mask:0xf bank_mask:0xf
	v_mul_f32_dpp v138, v138, v138 row_shr:8 row_mask:0xf bank_mask:0xf
	v_mul_f32_dpp v139, v139, v139 row_shr:8 row_mask:0xf bank_mask:0xf
	v_mul_f32_dpp v140, v140, v140 row_shr:8 row_mask:0xf bank_mask:0xf
	v_mul_f32_dpp v141, v141, v141 row_shr:8 row_mask:0xf bank_mask:0xf
	v_mul_f32_dpp v142, v142, v142 row_shr:8 row_mask:0xf bank_mask:0xf
	v_mul_f32_dpp v143, v143, v143 row_shr:8 row_mask:0xf bank_mask:0xf
	v_mul_f32_dpp v144, v144, v144 row_shr:8 row_mask:0xf bank_mask:0xf
	v_mul_f32_dpp v145, v145, v145 row_shr:8 row_mask:0xf bank_mask:0xf
	v_mul_f32_dpp v146, v146, v146 row_shr:8 row_mask:0xf bank_mask:0xf
	v_mul_f32_dpp v147, v147, v147 row_shr:8 row_mask:0xf bank_mask:0xf
	v_mul_f32_dpp v148, v148, v148 row_shr:8 row_mask:0xf bank_mask:0xf
	v_mul_f32_dpp v149, v149, v149 row_shr:8 row_mask:0xf bank_mask:0xf
	v_mul_f32_dpp v150, v150, v150 row_shr:8 row_mask:0xf bank_mask:0xf
	v_mul_f32_dpp v151, v151, v151 row_shr:8 row_mask:0xf bank_mask:0xf
	s_add_u32 m0, s1, 2048
	s_nop 0
	global_load_lds_dwordx4 v254, s[34:35]
	v_mul_f32_dpp v152, v152, v152 row_shr:8 row_mask:0xf bank_mask:0xf
	v_mul_f32_dpp v153, v153, v153 row_shr:8 row_mask:0xf bank_mask:0xf
	v_mul_f32_dpp v154, v154, v154 row_shr:8 row_mask:0xf bank_mask:0xf
	v_mul_f32_dpp v155, v155, v155 row_shr:8 row_mask:0xf bank_mask:0xf
	v_mul_f32_dpp v156, v156, v156 row_shr:8 row_mask:0xf bank_mask:0xf
	v_mul_f32_dpp v157, v157, v157 row_shr:8 row_mask:0xf bank_mask:0xf
	v_mul_f32_dpp v158, v158, v158 row_shr:8 row_mask:0xf bank_mask:0xf
	v_mul_f32_dpp v159, v159, v159 row_shr:8 row_mask:0xf bank_mask:0xf
	v_mul_f32_dpp v128, v128, v128 row_bcast:15 row_mask:0xa bank_mask:0xf
	v_mul_f32_dpp v129, v129, v129 row_bcast:15 row_mask:0xa bank_mask:0xf
	v_mul_f32_dpp v130, v130, v130 row_bcast:15 row_mask:0xa bank_mask:0xf
	v_mul_f32_dpp v131, v131, v131 row_bcast:15 row_mask:0xa bank_mask:0xf
	v_mul_f32_dpp v132, v132, v132 row_bcast:15 row_mask:0xa bank_mask:0xf
	v_mul_f32_dpp v133, v133, v133 row_bcast:15 row_mask:0xa bank_mask:0xf
	v_mul_f32_dpp v134, v134, v134 row_bcast:15 row_mask:0xa bank_mask:0xf
	v_mul_f32_dpp v135, v135, v135 row_bcast:15 row_mask:0xa bank_mask:0xf
	v_mul_f32_dpp v136, v136, v136 row_bcast:15 row_mask:0xa bank_mask:0xf
	v_mul_f32_dpp v137, v137, v137 row_bcast:15 row_mask:0xa bank_mask:0xf
	v_mul_f32_dpp v138, v138, v138 row_bcast:15 row_mask:0xa bank_mask:0xf
	v_mul_f32_dpp v139, v139, v139 row_bcast:15 row_mask:0xa bank_mask:0xf
	v_mul_f32_dpp v140, v140, v140 row_bcast:15 row_mask:0xa bank_mask:0xf
	v_mul_f32_dpp v141, v141, v141 row_bcast:15 row_mask:0xa bank_mask:0xf
	v_mul_f32_dpp v142, v142, v142 row_bcast:15 row_mask:0xa bank_mask:0xf
	v_mul_f32_dpp v143, v143, v143 row_bcast:15 row_mask:0xa bank_mask:0xf
	s_add_u32 m0, s1, 3072
	s_nop 0
	global_load_lds_dwordx4 v255, s[34:35]
	v_add_u32_e32 v252, s76, v252
	v_add_u32_e32 v253, s76, v253
	v_add_u32_e32 v254, s76, v254
	v_add_u32_e32 v255, s76, v255
	v_mul_f32_dpp v144, v144, v144 row_bcast:15 row_mask:0xa bank_mask:0xf
	v_mul_f32_dpp v145, v145, v145 row_bcast:15 row_mask:0xa bank_mask:0xf
	v_mul_f32_dpp v146, v146, v146 row_bcast:15 row_mask:0xa bank_mask:0xf
	v_mul_f32_dpp v147, v147, v147 row_bcast:15 row_mask:0xa bank_mask:0xf
	v_mul_f32_dpp v148, v148, v148 row_bcast:15 row_mask:0xa bank_mask:0xf
	v_mul_f32_dpp v149, v149, v149 row_bcast:15 row_mask:0xa bank_mask:0xf
	v_mul_f32_dpp v150, v150, v150 row_bcast:15 row_mask:0xa bank_mask:0xf
	v_mul_f32_dpp v151, v151, v151 row_bcast:15 row_mask:0xa bank_mask:0xf
	v_mul_f32_dpp v152, v152, v152 row_bcast:15 row_mask:0xa bank_mask:0xf
	v_mul_f32_dpp v153, v153, v153 row_bcast:15 row_mask:0xa bank_mask:0xf
	v_mul_f32_dpp v154, v154, v154 row_bcast:15 row_mask:0xa bank_mask:0xf
	v_mul_f32_dpp v155, v155, v155 row_bcast:15 row_mask:0xa bank_mask:0xf
	v_mul_f32_dpp v156, v156, v156 row_bcast:15 row_mask:0xa bank_mask:0xf
	v_mul_f32_dpp v157, v157, v157 row_bcast:15 row_mask:0xa bank_mask:0xf
	v_mul_f32_dpp v158, v158, v158 row_bcast:15 row_mask:0xa bank_mask:0xf
	v_mul_f32_dpp v159, v159, v159 row_bcast:15 row_mask:0xa bank_mask:0xf
	v_mul_f32_dpp v128, v128, v128 row_bcast:31 row_mask:0xc bank_mask:0xf
	v_mul_f32_dpp v129, v129, v129 row_bcast:31 row_mask:0xc bank_mask:0xf
	v_mul_f32_dpp v130, v130, v130 row_bcast:31 row_mask:0xc bank_mask:0xf
	v_mul_f32_dpp v131, v131, v131 row_bcast:31 row_mask:0xc bank_mask:0xf
	v_mul_f32_dpp v132, v132, v132 row_bcast:31 row_mask:0xc bank_mask:0xf
	v_mul_f32_dpp v133, v133, v133 row_bcast:31 row_mask:0xc bank_mask:0xf
	v_mul_f32_dpp v134, v134, v134 row_bcast:31 row_mask:0xc bank_mask:0xf
	v_mul_f32_dpp v135, v135, v135 row_bcast:31 row_mask:0xc bank_mask:0xf
	v_mul_f32_dpp v136, v136, v136 row_bcast:31 row_mask:0xc bank_mask:0xf
	v_mul_f32_dpp v137, v137, v137 row_bcast:31 row_mask:0xc bank_mask:0xf
	v_mul_f32_dpp v138, v138, v138 row_bcast:31 row_mask:0xc bank_mask:0xf
	v_mul_f32_dpp v139, v139, v139 row_bcast:31 row_mask:0xc bank_mask:0xf
	v_mul_f32_dpp v140, v140, v140 row_bcast:31 row_mask:0xc bank_mask:0xf
	v_mul_f32_dpp v141, v141, v141 row_bcast:31 row_mask:0xc bank_mask:0xf
	v_mul_f32_dpp v142, v142, v142 row_bcast:31 row_mask:0xc bank_mask:0xf
	v_mul_f32_dpp v143, v143, v143 row_bcast:31 row_mask:0xc bank_mask:0xf
	v_mul_f32_dpp v144, v144, v144 row_bcast:31 row_mask:0xc bank_mask:0xf
	v_mul_f32_dpp v145, v145, v145 row_bcast:31 row_mask:0xc bank_mask:0xf
	v_mul_f32_dpp v146, v146, v146 row_bcast:31 row_mask:0xc bank_mask:0xf
	v_mul_f32_dpp v147, v147, v147 row_bcast:31 row_mask:0xc bank_mask:0xf
	v_mul_f32_dpp v148, v148, v148 row_bcast:31 row_mask:0xc bank_mask:0xf
	v_mul_f32_dpp v149, v149, v149 row_bcast:31 row_mask:0xc bank_mask:0xf
	v_mul_f32_dpp v150, v150, v150 row_bcast:31 row_mask:0xc bank_mask:0xf
	v_mul_f32_dpp v151, v151, v151 row_bcast:31 row_mask:0xc bank_mask:0xf
	v_mul_f32_dpp v152, v152, v152 row_bcast:31 row_mask:0xc bank_mask:0xf
	v_mul_f32_dpp v153, v153, v153 row_bcast:31 row_mask:0xc bank_mask:0xf
	v_mul_f32_dpp v154, v154, v154 row_bcast:31 row_mask:0xc bank_mask:0xf
	v_mul_f32_dpp v155, v155, v155 row_bcast:31 row_mask:0xc bank_mask:0xf
	v_mul_f32_dpp v156, v156, v156 row_bcast:31 row_mask:0xc bank_mask:0xf
	v_mul_f32_dpp v157, v157, v157 row_bcast:31 row_mask:0xc bank_mask:0xf
	v_mul_f32_dpp v158, v158, v158 row_bcast:31 row_mask:0xc bank_mask:0xf
	v_mul_f32_dpp v159, v159, v159 row_bcast:31 row_mask:0xc bank_mask:0xf
	s_mov_b32 exec_lo, 0
	s_brev_b32 exec_hi, 1
	ds_write_b128 v247, v[128:131] offset:0
	ds_write_b128 v247, v[132:135] offset:16
	ds_write_b128 v247, v[136:139] offset:32
	ds_write_b128 v247, v[140:143] offset:48
	ds_write_b128 v247, v[144:147] offset:64
	ds_write_b128 v247, v[148:151] offset:80
	ds_write_b128 v247, v[152:155] offset:96
	ds_write_b128 v247, v[156:159] offset:112
	s_mov_b64 exec, -1
	v_rcp_f32_e32 v220, v128
	v_rcp_f32_e32 v221, v129
	v_lshlrev_b32_e32 v218, 16, v0
	v_and_b32_e32 v219, 0xffff0000, v0
	v_pk_mul_f32 v[218:219], v[128:129], v[218:219]
	v_pk_mul_f32 v[220:221], v[220:221], v[96:97]
	v_cvt_pk_bf16_f32 v202, v218, v219
	v_cvt_pk_bf16_f32 v184, v220, v221
	v_rcp_f32_e32 v220, v130
	v_rcp_f32_e32 v221, v131
	v_lshlrev_b32_e32 v218, 16, v1
	v_and_b32_e32 v219, 0xffff0000, v1
	v_pk_mul_f32 v[218:219], v[130:131], v[218:219]
	v_pk_mul_f32 v[220:221], v[220:221], v[98:99]
	v_cvt_pk_bf16_f32 v203, v218, v219
	v_cvt_pk_bf16_f32 v185, v220, v221
	v_rcp_f32_e32 v220, v132
	v_rcp_f32_e32 v221, v133
	v_lshlrev_b32_e32 v218, 16, v2
	v_and_b32_e32 v219, 0xffff0000, v2
	v_pk_mul_f32 v[218:219], v[132:133], v[218:219]
	v_pk_mul_f32 v[220:221], v[220:221], v[100:101]
	v_cvt_pk_bf16_f32 v204, v218, v219
	v_cvt_pk_bf16_f32 v186, v220, v221
	v_rcp_f32_e32 v220, v134
	v_rcp_f32_e32 v221, v135
	v_lshlrev_b32_e32 v218, 16, v3
	v_and_b32_e32 v219, 0xffff0000, v3
	v_pk_mul_f32 v[218:219], v[134:135], v[218:219]
	v_pk_mul_f32 v[220:221], v[220:221], v[102:103]
	v_cvt_pk_bf16_f32 v205, v218, v219
	v_cvt_pk_bf16_f32 v187, v220, v221
	global_load_dwordx4 v[0:3], v228, s[30:31]
	v_rcp_f32_e32 v220, v136
	v_rcp_f32_e32 v221, v137
	v_lshlrev_b32_e32 v218, 16, v4
	v_and_b32_e32 v219, 0xffff0000, v4
	v_pk_mul_f32 v[218:219], v[136:137], v[218:219]
	v_pk_mul_f32 v[220:221], v[220:221], v[104:105]
	v_cvt_pk_bf16_f32 v206, v218, v219
	v_cvt_pk_bf16_f32 v188, v220, v221
	v_rcp_f32_e32 v220, v138
	v_rcp_f32_e32 v221, v139
	v_lshlrev_b32_e32 v218, 16, v5
	v_and_b32_e32 v219, 0xffff0000, v5
	v_pk_mul_f32 v[218:219], v[138:139], v[218:219]
	v_pk_mul_f32 v[220:221], v[220:221], v[106:107]
	v_cvt_pk_bf16_f32 v207, v218, v219
	v_cvt_pk_bf16_f32 v189, v220, v221
	v_rcp_f32_e32 v220, v140
	v_rcp_f32_e32 v221, v141
	v_lshlrev_b32_e32 v218, 16, v6
	v_and_b32_e32 v219, 0xffff0000, v6
	v_pk_mul_f32 v[218:219], v[140:141], v[218:219]
	v_pk_mul_f32 v[220:221], v[220:221], v[108:109]
	v_cvt_pk_bf16_f32 v208, v218, v219
	v_cvt_pk_bf16_f32 v190, v220, v221
	v_rcp_f32_e32 v220, v142
	v_rcp_f32_e32 v221, v143
	v_lshlrev_b32_e32 v218, 16, v7
	v_and_b32_e32 v219, 0xffff0000, v7
	v_pk_mul_f32 v[218:219], v[142:143], v[218:219]
	v_pk_mul_f32 v[220:221], v[220:221], v[110:111]
	v_cvt_pk_bf16_f32 v209, v218, v219
	v_cvt_pk_bf16_f32 v191, v220, v221
	global_load_dwordx4 v[4:7], v228, s[30:31] offset:16
	v_rcp_f32_e32 v220, v144
	v_rcp_f32_e32 v221, v145
	v_lshlrev_b32_e32 v218, 16, v8
	v_and_b32_e32 v219, 0xffff0000, v8
	v_pk_mul_f32 v[218:219], v[144:145], v[218:219]
	v_pk_mul_f32 v[220:221], v[220:221], v[112:113]
	v_cvt_pk_bf16_f32 v210, v218, v219
	v_cvt_pk_bf16_f32 v192, v220, v221
	v_rcp_f32_e32 v220, v146
	v_rcp_f32_e32 v221, v147
	v_lshlrev_b32_e32 v218, 16, v9
	v_and_b32_e32 v219, 0xffff0000, v9
	v_pk_mul_f32 v[218:219], v[146:147], v[218:219]
	v_pk_mul_f32 v[220:221], v[220:221], v[114:115]
	v_cvt_pk_bf16_f32 v211, v218, v219
	v_cvt_pk_bf16_f32 v193, v220, v221
	v_rcp_f32_e32 v220, v148
	v_rcp_f32_e32 v221, v149
	v_lshlrev_b32_e32 v218, 16, v10
	v_and_b32_e32 v219, 0xffff0000, v10
	v_pk_mul_f32 v[218:219], v[148:149], v[218:219]
	v_pk_mul_f32 v[220:221], v[220:221], v[116:117]
	v_cvt_pk_bf16_f32 v212, v218, v219
	v_cvt_pk_bf16_f32 v194, v220, v221
	v_rcp_f32_e32 v220, v150
	v_rcp_f32_e32 v221, v151
	v_lshlrev_b32_e32 v218, 16, v11
	v_and_b32_e32 v219, 0xffff0000, v11
	v_pk_mul_f32 v[218:219], v[150:151], v[218:219]
	v_pk_mul_f32 v[220:221], v[220:221], v[118:119]
	v_cvt_pk_bf16_f32 v213, v218, v219
	v_cvt_pk_bf16_f32 v195, v220, v221
	global_load_dwordx4 v[8:11], v228, s[30:31] offset:32
	v_rcp_f32_e32 v220, v152
	v_rcp_f32_e32 v221, v153
	v_lshlrev_b32_e32 v218, 16, v12
	v_and_b32_e32 v219, 0xffff0000, v12
	v_pk_mul_f32 v[218:219], v[152:153], v[218:219]
	v_pk_mul_f32 v[220:221], v[220:221], v[120:121]
	v_cvt_pk_bf16_f32 v214, v218, v219
	v_cvt_pk_bf16_f32 v196, v220, v221
	v_rcp_f32_e32 v220, v154
	v_rcp_f32_e32 v221, v155
	v_lshlrev_b32_e32 v218, 16, v13
	v_and_b32_e32 v219, 0xffff0000, v13
	v_pk_mul_f32 v[218:219], v[154:155], v[218:219]
	v_pk_mul_f32 v[220:221], v[220:221], v[122:123]
	v_cvt_pk_bf16_f32 v215, v218, v219
	v_cvt_pk_bf16_f32 v197, v220, v221
	v_rcp_f32_e32 v220, v156
	v_rcp_f32_e32 v221, v157
	v_lshlrev_b32_e32 v218, 16, v14
	v_and_b32_e32 v219, 0xffff0000, v14
	v_pk_mul_f32 v[218:219], v[156:157], v[218:219]
	v_pk_mul_f32 v[220:221], v[220:221], v[124:125]
	v_cvt_pk_bf16_f32 v216, v218, v219
	v_cvt_pk_bf16_f32 v198, v220, v221
	v_rcp_f32_e32 v220, v158
	v_rcp_f32_e32 v221, v159
	v_lshlrev_b32_e32 v218, 16, v15
	v_and_b32_e32 v219, 0xffff0000, v15
	v_pk_mul_f32 v[218:219], v[158:159], v[218:219]
	v_pk_mul_f32 v[220:221], v[220:221], v[126:127]
	v_cvt_pk_bf16_f32 v217, v218, v219
	v_cvt_pk_bf16_f32 v199, v220, v221
	global_load_dwordx4 v[12:15], v228, s[30:31] offset:48
	v_add_u32_e32 v228, s76, v228
	ds_write_b128 v222, v[184:187] offset:1024
	ds_write_b128 v223, v[188:191] offset:1024
	ds_write_b128 v224, v[192:195] offset:1024
	ds_write_b128 v225, v[196:199] offset:1024
	ds_write_b128 v226, v[202:205]
	ds_write_b128 v226, v[206:209] offset:16
	ds_write_b128 v226, v[210:213] offset:32
	ds_write_b128 v226, v[214:217] offset:48
	s_waitcnt lgkmcnt(0)
	s_barrier
	s_waitcnt vmcnt(12)
	s_cmp_ge_u32 s70, 30
	s_cselect_b32 s76, 0, s33
	s_add_u32 s1, s72, s77
	s_add_u32 s77, s77, 0x4000
	s_cmp_eq_u32 s77, 0x10400
	s_cselect_b32 s77, 0x1b400, s77
	s_cmp_eq_u32 s77, 0x23400
	s_cselect_b32 s77, 0x8400, s77
	v_lshlrev_b32_e32 v96, 16, v32
	v_and_b32_e32 v97, 0xffff0000, v32
	v_lshlrev_b32_e32 v98, 16, v33
	v_and_b32_e32 v99, 0xffff0000, v33
	v_lshlrev_b32_e32 v100, 16, v34
	v_and_b32_e32 v101, 0xffff0000, v34
	v_lshlrev_b32_e32 v102, 16, v35
	v_and_b32_e32 v103, 0xffff0000, v35
	v_lshlrev_b32_e32 v104, 16, v36
	v_and_b32_e32 v105, 0xffff0000, v36
	v_lshlrev_b32_e32 v106, 16, v37
	v_and_b32_e32 v107, 0xffff0000, v37
	v_lshlrev_b32_e32 v108, 16, v38
	v_and_b32_e32 v109, 0xffff0000, v38
	v_lshlrev_b32_e32 v110, 16, v39
	v_and_b32_e32 v111, 0xffff0000, v39
	v_lshlrev_b32_e32 v112, 16, v40
	v_and_b32_e32 v113, 0xffff0000, v40
	v_lshlrev_b32_e32 v114, 16, v41
	v_and_b32_e32 v115, 0xffff0000, v41
	v_lshlrev_b32_e32 v116, 16, v42
	v_and_b32_e32 v117, 0xffff0000, v42
	v_lshlrev_b32_e32 v118, 16, v43
	v_and_b32_e32 v119, 0xffff0000, v43
	v_lshlrev_b32_e32 v120, 16, v44
	v_and_b32_e32 v121, 0xffff0000, v44
	v_lshlrev_b32_e32 v122, 16, v45
	v_and_b32_e32 v123, 0xffff0000, v45
	v_lshlrev_b32_e32 v124, 16, v46
	v_and_b32_e32 v125, 0xffff0000, v46
	v_lshlrev_b32_e32 v126, 16, v47
	v_and_b32_e32 v127, 0xffff0000, v47
	v_sub_f32_e32 v128, 1.0, v96
	v_sub_f32_e32 v129, 1.0, v97
	v_sub_f32_e32 v130, 1.0, v98
	v_sub_f32_e32 v131, 1.0, v99
	v_sub_f32_e32 v132, 1.0, v100
	v_sub_f32_e32 v133, 1.0, v101
	v_sub_f32_e32 v134, 1.0, v102
	v_sub_f32_e32 v135, 1.0, v103
	global_load_dwordx4 v[32:35], v228, s[14:15]
	v_sub_f32_e32 v136, 1.0, v104
	v_sub_f32_e32 v137, 1.0, v105
	v_sub_f32_e32 v138, 1.0, v106
	v_sub_f32_e32 v139, 1.0, v107
	v_sub_f32_e32 v140, 1.0, v108
	v_sub_f32_e32 v141, 1.0, v109
	v_sub_f32_e32 v142, 1.0, v110
	v_sub_f32_e32 v143, 1.0, v111
	v_sub_f32_e32 v144, 1.0, v112
	v_sub_f32_e32 v145, 1.0, v113
	v_sub_f32_e32 v146, 1.0, v114
	v_sub_f32_e32 v147, 1.0, v115
	v_sub_f32_e32 v148, 1.0, v116
	v_sub_f32_e32 v149, 1.0, v117
	v_sub_f32_e32 v150, 1.0, v118
	v_sub_f32_e32 v151, 1.0, v119
	v_sub_f32_e32 v152, 1.0, v120
	v_sub_f32_e32 v153, 1.0, v121
	v_sub_f32_e32 v154, 1.0, v122
	v_sub_f32_e32 v155, 1.0, v123
	v_sub_f32_e32 v156, 1.0, v124
	v_sub_f32_e32 v157, 1.0, v125
	v_sub_f32_e32 v158, 1.0, v126
	v_sub_f32_e32 v159, 1.0, v127
	global_load_dwordx4 v[36:39], v228, s[14:15] offset:16
	v_mul_f32_dpp v128, v128, v128 row_shr:1 row_mask:0xf bank_mask:0xf
	v_mul_f32_dpp v129, v129, v129 row_shr:1 row_mask:0xf bank_mask:0xf
	v_mul_f32_dpp v130, v130, v130 row_shr:1 row_mask:0xf bank_mask:0xf
	v_mul_f32_dpp v131, v131, v131 row_shr:1 row_mask:0xf bank_mask:0xf
	v_mul_f32_dpp v132, v132, v132 row_shr:1 row_mask:0xf bank_mask:0xf
	v_mul_f32_dpp v133, v133, v133 row_shr:1 row_mask:0xf bank_mask:0xf
	v_mul_f32_dpp v134, v134, v134 row_shr:1 row_mask:0xf bank_mask:0xf
	v_mul_f32_dpp v135, v135, v135 row_shr:1 row_mask:0xf bank_mask:0xf
	v_mul_f32_dpp v136, v136, v136 row_shr:1 row_mask:0xf bank_mask:0xf
	v_mul_f32_dpp v137, v137, v137 row_shr:1 row_mask:0xf bank_mask:0xf
	v_mul_f32_dpp v138, v138, v138 row_shr:1 row_mask:0xf bank_mask:0xf
	v_mul_f32_dpp v139, v139, v139 row_shr:1 row_mask:0xf bank_mask:0xf
	v_mul_f32_dpp v140, v140, v140 row_shr:1 row_mask:0xf bank_mask:0xf
	v_mul_f32_dpp v141, v141, v141 row_shr:1 row_mask:0xf bank_mask:0xf
	v_mul_f32_dpp v142, v142, v142 row_shr:1 row_mask:0xf bank_mask:0xf
	v_mul_f32_dpp v143, v143, v143 row_shr:1 row_mask:0xf bank_mask:0xf
	v_mul_f32_dpp v144, v144, v144 row_shr:1 row_mask:0xf bank_mask:0xf
	v_mul_f32_dpp v145, v145, v145 row_shr:1 row_mask:0xf bank_mask:0xf
	v_mul_f32_dpp v146, v146, v146 row_shr:1 row_mask:0xf bank_mask:0xf
	v_mul_f32_dpp v147, v147, v147 row_shr:1 row_mask:0xf bank_mask:0xf
	v_mul_f32_dpp v148, v148, v148 row_shr:1 row_mask:0xf bank_mask:0xf
	v_mul_f32_dpp v149, v149, v149 row_shr:1 row_mask:0xf bank_mask:0xf
	v_mul_f32_dpp v150, v150, v150 row_shr:1 row_mask:0xf bank_mask:0xf
	v_mul_f32_dpp v151, v151, v151 row_shr:1 row_mask:0xf bank_mask:0xf
	global_load_dwordx4 v[40:43], v228, s[14:15] offset:32
	v_mul_f32_dpp v152, v152, v152 row_shr:1 row_mask:0xf bank_mask:0xf
	v_mul_f32_dpp v153, v153, v153 row_shr:1 row_mask:0xf bank_mask:0xf
	v_mul_f32_dpp v154, v154, v154 row_shr:1 row_mask:0xf bank_mask:0xf
	v_mul_f32_dpp v155, v155, v155 row_shr:1 row_mask:0xf bank_mask:0xf
	v_mul_f32_dpp v156, v156, v156 row_shr:1 row_mask:0xf bank_mask:0xf
	v_mul_f32_dpp v157, v157, v157 row_shr:1 row_mask:0xf bank_mask:0xf
	v_mul_f32_dpp v158, v158, v158 row_shr:1 row_mask:0xf bank_mask:0xf
	v_mul_f32_dpp v159, v159, v159 row_shr:1 row_mask:0xf bank_mask:0xf
	v_mul_f32_dpp v128, v128, v128 row_shr:2 row_mask:0xf bank_mask:0xf
	v_mul_f32_dpp v129, v129, v129 row_shr:2 row_mask:0xf bank_mask:0xf
	v_mul_f32_dpp v130, v130, v130 row_shr:2 row_mask:0xf bank_mask:0xf
	v_mul_f32_dpp v131, v131, v131 row_shr:2 row_mask:0xf bank_mask:0xf
	v_mul_f32_dpp v132, v132, v132 row_shr:2 row_mask:0xf bank_mask:0xf
	v_mul_f32_dpp v133, v133, v133 row_shr:2 row_mask:0xf bank_mask:0xf
	v_mul_f32_dpp v134, v134, v134 row_shr:2 row_mask:0xf bank_mask:0xf
	v_mul_f32_dpp v135, v135, v135 row_shr:2 row_mask:0xf bank_mask:0xf
	v_mul_f32_dpp v136, v136, v136 row_shr:2 row_mask:0xf bank_mask:0xf
	v_mul_f32_dpp v137, v137, v137 row_shr:2 row_mask:0xf bank_mask:0xf
	v_mul_f32_dpp v138, v138, v138 row_shr:2 row_mask:0xf bank_mask:0xf
	v_mul_f32_dpp v139, v139, v139 row_shr:2 row_mask:0xf bank_mask:0xf
	v_mul_f32_dpp v140, v140, v140 row_shr:2 row_mask:0xf bank_mask:0xf
	v_mul_f32_dpp v141, v141, v141 row_shr:2 row_mask:0xf bank_mask:0xf
	v_mul_f32_dpp v142, v142, v142 row_shr:2 row_mask:0xf bank_mask:0xf
	v_mul_f32_dpp v143, v143, v143 row_shr:2 row_mask:0xf bank_mask:0xf
	global_load_dwordx4 v[44:47], v228, s[14:15] offset:48
	v_mul_f32_dpp v144, v144, v144 row_shr:2 row_mask:0xf bank_mask:0xf
	v_mul_f32_dpp v145, v145, v145 row_shr:2 row_mask:0xf bank_mask:0xf
	v_mul_f32_dpp v146, v146, v146 row_shr:2 row_mask:0xf bank_mask:0xf
	v_mul_f32_dpp v147, v147, v147 row_shr:2 row_mask:0xf bank_mask:0xf
	v_mul_f32_dpp v148, v148, v148 row_shr:2 row_mask:0xf bank_mask:0xf
	v_mul_f32_dpp v149, v149, v149 row_shr:2 row_mask:0xf bank_mask:0xf
	v_mul_f32_dpp v150, v150, v150 row_shr:2 row_mask:0xf bank_mask:0xf
	v_mul_f32_dpp v151, v151, v151 row_shr:2 row_mask:0xf bank_mask:0xf
	v_mul_f32_dpp v152, v152, v152 row_shr:2 row_mask:0xf bank_mask:0xf
	v_mul_f32_dpp v153, v153, v153 row_shr:2 row_mask:0xf bank_mask:0xf
	v_mul_f32_dpp v154, v154, v154 row_shr:2 row_mask:0xf bank_mask:0xf
	v_mul_f32_dpp v155, v155, v155 row_shr:2 row_mask:0xf bank_mask:0xf
	v_mul_f32_dpp v156, v156, v156 row_shr:2 row_mask:0xf bank_mask:0xf
	v_mul_f32_dpp v157, v157, v157 row_shr:2 row_mask:0xf bank_mask:0xf
	v_mul_f32_dpp v158, v158, v158 row_shr:2 row_mask:0xf bank_mask:0xf
	v_mul_f32_dpp v159, v159, v159 row_shr:2 row_mask:0xf bank_mask:0xf
	v_mul_f32_dpp v128, v128, v128 row_shr:4 row_mask:0xf bank_mask:0xf
	v_mul_f32_dpp v129, v129, v129 row_shr:4 row_mask:0xf bank_mask:0xf
	v_mul_f32_dpp v130, v130, v130 row_shr:4 row_mask:0xf bank_mask:0xf
	v_mul_f32_dpp v131, v131, v131 row_shr:4 row_mask:0xf bank_mask:0xf
	v_mul_f32_dpp v132, v132, v132 row_shr:4 row_mask:0xf bank_mask:0xf
	v_mul_f32_dpp v133, v133, v133 row_shr:4 row_mask:0xf bank_mask:0xf
	v_mul_f32_dpp v134, v134, v134 row_shr:4 row_mask:0xf bank_mask:0xf
	v_mul_f32_dpp v135, v135, v135 row_shr:4 row_mask:0xf bank_mask:0xf
	s_add_u32 m0, s1, 0
	s_nop 0
	global_load_lds_dwordx4 v252, s[34:35]
	v_mul_f32_dpp v136, v136, v136 row_shr:4 row_mask:0xf bank_mask:0xf
	v_mul_f32_dpp v137, v137, v137 row_shr:4 row_mask:0xf bank_mask:0xf
	v_mul_f32_dpp v138, v138, v138 row_shr:4 row_mask:0xf bank_mask:0xf
	v_mul_f32_dpp v139, v139, v139 row_shr:4 row_mask:0xf bank_mask:0xf
	v_mul_f32_dpp v140, v140, v140 row_shr:4 row_mask:0xf bank_mask:0xf
	v_mul_f32_dpp v141, v141, v141 row_shr:4 row_mask:0xf bank_mask:0xf
	v_mul_f32_dpp v142, v142, v142 row_shr:4 row_mask:0xf bank_mask:0xf
	v_mul_f32_dpp v143, v143, v143 row_shr:4 row_mask:0xf bank_mask:0xf
	v_mul_f32_dpp v144, v144, v144 row_shr:4 row_mask:0xf bank_mask:0xf
	v_mul_f32_dpp v145, v145, v145 row_shr:4 row_mask:0xf bank_mask:0xf
	v_mul_f32_dpp v146, v146, v146 row_shr:4 row_mask:0xf bank_mask:0xf
	v_mul_f32_dpp v147, v147, v147 row_shr:4 row_mask:0xf bank_mask:0xf
	v_mul_f32_dpp v148, v148, v148 row_shr:4 row_mask:0xf bank_mask:0xf
	v_mul_f32_dpp v149, v149, v149 row_shr:4 row_mask:0xf bank_mask:0xf
	v_mul_f32_dpp v150, v150, v150 row_shr:4 row_mask:0xf bank_mask:0xf
	v_mul_f32_dpp v151, v151, v151 row_shr:4 row_mask:0xf bank_mask:0xf
	v_mul_f32_dpp v152, v152, v152 row_shr:4 row_mask:0xf bank_mask:0xf
	v_mul_f32_dpp v153, v153, v153 row_shr:4 row_mask:0xf bank_mask:0xf
	v_mul_f32_dpp v154, v154, v154 row_shr:4 row_mask:0xf bank_mask:0xf
	v_mul_f32_dpp v155, v155, v155 row_shr:4 row_mask:0xf bank_mask:0xf
	v_mul_f32_dpp v156, v156, v156 row_shr:4 row_mask:0xf bank_mask:0xf
	v_mul_f32_dpp v157, v157, v157 row_shr:4 row_mask:0xf bank_mask:0xf
	v_mul_f32_dpp v158, v158, v158 row_shr:4 row_mask:0xf bank_mask:0xf
	v_mul_f32_dpp v159, v159, v159 row_shr:4 row_mask:0xf bank_mask:0xf
	s_add_u32 m0, s1, 1024
	s_nop 0
	global_load_lds_dwordx4 v253, s[34:35]
	v_mul_f32_dpp v128, v128, v128 row_shr:8 row_mask:0xf bank_mask:0xf
	v_mul_f32_dpp v129, v129, v129 row_shr:8 row_mask:0xf bank_mask:0xf
	v_mul_f32_dpp v130, v130, v130 row_shr:8 row_mask:0xf bank_mask:0xf
	v_mul_f32_dpp v131, v131, v131 row_shr:8 row_mask:0xf bank_mask:0xf
	v_mul_f32_dpp v132, v132, v132 row_shr:8 row_mask:0xf bank_mask:0xf
	v_mul_f32_dpp v133, v133, v133 row_shr:8 row_mask:0xf bank_mask:0xf
	v_mul_f32_dpp v134, v134, v134 row_shr:8 row_mask:0xf bank_mask:0xf
	v_mul_f32_dpp v135, v135, v135 row_shr:8 row_mask:0xf bank_mask:0xf
	v_mul_f32_dpp v136, v136, v136 row_shr:8 row_mask:0xf bank_mask:0xf
	v_mul_f32_dpp v137, v137, v137 row_shr:8 row_mask:0xf bank_mask:0xf
	v_mul_f32_dpp v138, v138, v138 row_shr:8 row_mask:0xf bank_mask:0xf
	v_mul_f32_dpp v139, v139, v139 row_shr:8 row_mask:0xf bank_mask:0xf
	v_mul_f32_dpp v140, v140, v140 row_shr:8 row_mask:0xf bank_mask:0xf
	v_mul_f32_dpp v141, v141, v141 row_shr:8 row_mask:0xf bank_mask:0xf
	v_mul_f32_dpp v142, v142, v142 row_shr:8 row_mask:0xf bank_mask:0xf
	v_mul_f32_dpp v143, v143, v143 row_shr:8 row_mask:0xf bank_mask:0xf
	v_mul_f32_dpp v144, v144, v144 row_shr:8 row_mask:0xf bank_mask:0xf
	v_mul_f32_dpp v145, v145, v145 row_shr:8 row_mask:0xf bank_mask:0xf
	v_mul_f32_dpp v146, v146, v146 row_shr:8 row_mask:0xf bank_mask:0xf
	v_mul_f32_dpp v147, v147, v147 row_shr:8 row_mask:0xf bank_mask:0xf
	v_mul_f32_dpp v148, v148, v148 row_shr:8 row_mask:0xf bank_mask:0xf
	v_mul_f32_dpp v149, v149, v149 row_shr:8 row_mask:0xf bank_mask:0xf
	v_mul_f32_dpp v150, v150, v150 row_shr:8 row_mask:0xf bank_mask:0xf
	v_mul_f32_dpp v151, v151, v151 row_shr:8 row_mask:0xf bank_mask:0xf
	s_add_u32 m0, s1, 2048
	s_nop 0
	global_load_lds_dwordx4 v254, s[34:35]
	v_mul_f32_dpp v152, v152, v152 row_shr:8 row_mask:0xf bank_mask:0xf
	v_mul_f32_dpp v153, v153, v153 row_shr:8 row_mask:0xf bank_mask:0xf
	v_mul_f32_dpp v154, v154, v154 row_shr:8 row_mask:0xf bank_mask:0xf
	v_mul_f32_dpp v155, v155, v155 row_shr:8 row_mask:0xf bank_mask:0xf
	v_mul_f32_dpp v156, v156, v156 row_shr:8 row_mask:0xf bank_mask:0xf
	v_mul_f32_dpp v157, v157, v157 row_shr:8 row_mask:0xf bank_mask:0xf
	v_mul_f32_dpp v158, v158, v158 row_shr:8 row_mask:0xf bank_mask:0xf
	v_mul_f32_dpp v159, v159, v159 row_shr:8 row_mask:0xf bank_mask:0xf
	v_mul_f32_dpp v128, v128, v128 row_bcast:15 row_mask:0xa bank_mask:0xf
	v_mul_f32_dpp v129, v129, v129 row_bcast:15 row_mask:0xa bank_mask:0xf
	v_mul_f32_dpp v130, v130, v130 row_bcast:15 row_mask:0xa bank_mask:0xf
	v_mul_f32_dpp v131, v131, v131 row_bcast:15 row_mask:0xa bank_mask:0xf
	v_mul_f32_dpp v132, v132, v132 row_bcast:15 row_mask:0xa bank_mask:0xf
	v_mul_f32_dpp v133, v133, v133 row_bcast:15 row_mask:0xa bank_mask:0xf
	v_mul_f32_dpp v134, v134, v134 row_bcast:15 row_mask:0xa bank_mask:0xf
	v_mul_f32_dpp v135, v135, v135 row_bcast:15 row_mask:0xa bank_mask:0xf
	v_mul_f32_dpp v136, v136, v136 row_bcast:15 row_mask:0xa bank_mask:0xf
	v_mul_f32_dpp v137, v137, v137 row_bcast:15 row_mask:0xa bank_mask:0xf
	v_mul_f32_dpp v138, v138, v138 row_bcast:15 row_mask:0xa bank_mask:0xf
	v_mul_f32_dpp v139, v139, v139 row_bcast:15 row_mask:0xa bank_mask:0xf
	v_mul_f32_dpp v140, v140, v140 row_bcast:15 row_mask:0xa bank_mask:0xf
	v_mul_f32_dpp v141, v141, v141 row_bcast:15 row_mask:0xa bank_mask:0xf
	v_mul_f32_dpp v142, v142, v142 row_bcast:15 row_mask:0xa bank_mask:0xf
	v_mul_f32_dpp v143, v143, v143 row_bcast:15 row_mask:0xa bank_mask:0xf
	s_add_u32 m0, s1, 3072
	s_nop 0
	global_load_lds_dwordx4 v255, s[34:35]
	v_add_u32_e32 v252, s76, v252
	v_add_u32_e32 v253, s76, v253
	v_add_u32_e32 v254, s76, v254
	v_add_u32_e32 v255, s76, v255
	v_mul_f32_dpp v144, v144, v144 row_bcast:15 row_mask:0xa bank_mask:0xf
	v_mul_f32_dpp v145, v145, v145 row_bcast:15 row_mask:0xa bank_mask:0xf
	v_mul_f32_dpp v146, v146, v146 row_bcast:15 row_mask:0xa bank_mask:0xf
	v_mul_f32_dpp v147, v147, v147 row_bcast:15 row_mask:0xa bank_mask:0xf
	v_mul_f32_dpp v148, v148, v148 row_bcast:15 row_mask:0xa bank_mask:0xf
	v_mul_f32_dpp v149, v149, v149 row_bcast:15 row_mask:0xa bank_mask:0xf
	v_mul_f32_dpp v150, v150, v150 row_bcast:15 row_mask:0xa bank_mask:0xf
	v_mul_f32_dpp v151, v151, v151 row_bcast:15 row_mask:0xa bank_mask:0xf
	v_mul_f32_dpp v152, v152, v152 row_bcast:15 row_mask:0xa bank_mask:0xf
	v_mul_f32_dpp v153, v153, v153 row_bcast:15 row_mask:0xa bank_mask:0xf
	v_mul_f32_dpp v154, v154, v154 row_bcast:15 row_mask:0xa bank_mask:0xf
	v_mul_f32_dpp v155, v155, v155 row_bcast:15 row_mask:0xa bank_mask:0xf
	v_mul_f32_dpp v156, v156, v156 row_bcast:15 row_mask:0xa bank_mask:0xf
	v_mul_f32_dpp v157, v157, v157 row_bcast:15 row_mask:0xa bank_mask:0xf
	v_mul_f32_dpp v158, v158, v158 row_bcast:15 row_mask:0xa bank_mask:0xf
	v_mul_f32_dpp v159, v159, v159 row_bcast:15 row_mask:0xa bank_mask:0xf
	v_mul_f32_dpp v128, v128, v128 row_bcast:31 row_mask:0xc bank_mask:0xf
	v_mul_f32_dpp v129, v129, v129 row_bcast:31 row_mask:0xc bank_mask:0xf
	v_mul_f32_dpp v130, v130, v130 row_bcast:31 row_mask:0xc bank_mask:0xf
	v_mul_f32_dpp v131, v131, v131 row_bcast:31 row_mask:0xc bank_mask:0xf
	v_mul_f32_dpp v132, v132, v132 row_bcast:31 row_mask:0xc bank_mask:0xf
	v_mul_f32_dpp v133, v133, v133 row_bcast:31 row_mask:0xc bank_mask:0xf
	v_mul_f32_dpp v134, v134, v134 row_bcast:31 row_mask:0xc bank_mask:0xf
	v_mul_f32_dpp v135, v135, v135 row_bcast:31 row_mask:0xc bank_mask:0xf
	v_mul_f32_dpp v136, v136, v136 row_bcast:31 row_mask:0xc bank_mask:0xf
	v_mul_f32_dpp v137, v137, v137 row_bcast:31 row_mask:0xc bank_mask:0xf
	v_mul_f32_dpp v138, v138, v138 row_bcast:31 row_mask:0xc bank_mask:0xf
	v_mul_f32_dpp v139, v139, v139 row_bcast:31 row_mask:0xc bank_mask:0xf
	v_mul_f32_dpp v140, v140, v140 row_bcast:31 row_mask:0xc bank_mask:0xf
	v_mul_f32_dpp v141, v141, v141 row_bcast:31 row_mask:0xc bank_mask:0xf
	v_mul_f32_dpp v142, v142, v142 row_bcast:31 row_mask:0xc bank_mask:0xf
	v_mul_f32_dpp v143, v143, v143 row_bcast:31 row_mask:0xc bank_mask:0xf
	v_mul_f32_dpp v144, v144, v144 row_bcast:31 row_mask:0xc bank_mask:0xf
	v_mul_f32_dpp v145, v145, v145 row_bcast:31 row_mask:0xc bank_mask:0xf
	v_mul_f32_dpp v146, v146, v146 row_bcast:31 row_mask:0xc bank_mask:0xf
	v_mul_f32_dpp v147, v147, v147 row_bcast:31 row_mask:0xc bank_mask:0xf
	v_mul_f32_dpp v148, v148, v148 row_bcast:31 row_mask:0xc bank_mask:0xf
	v_mul_f32_dpp v149, v149, v149 row_bcast:31 row_mask:0xc bank_mask:0xf
	v_mul_f32_dpp v150, v150, v150 row_bcast:31 row_mask:0xc bank_mask:0xf
	v_mul_f32_dpp v151, v151, v151 row_bcast:31 row_mask:0xc bank_mask:0xf
	v_mul_f32_dpp v152, v152, v152 row_bcast:31 row_mask:0xc bank_mask:0xf
	v_mul_f32_dpp v153, v153, v153 row_bcast:31 row_mask:0xc bank_mask:0xf
	v_mul_f32_dpp v154, v154, v154 row_bcast:31 row_mask:0xc bank_mask:0xf
	v_mul_f32_dpp v155, v155, v155 row_bcast:31 row_mask:0xc bank_mask:0xf
	v_mul_f32_dpp v156, v156, v156 row_bcast:31 row_mask:0xc bank_mask:0xf
	v_mul_f32_dpp v157, v157, v157 row_bcast:31 row_mask:0xc bank_mask:0xf
	v_mul_f32_dpp v158, v158, v158 row_bcast:31 row_mask:0xc bank_mask:0xf
	v_mul_f32_dpp v159, v159, v159 row_bcast:31 row_mask:0xc bank_mask:0xf
	s_mov_b32 exec_lo, 0
	s_brev_b32 exec_hi, 1
	ds_write_b128 v247, v[128:131] offset:512
	ds_write_b128 v247, v[132:135] offset:528
	ds_write_b128 v247, v[136:139] offset:544
	ds_write_b128 v247, v[140:143] offset:560
	ds_write_b128 v247, v[144:147] offset:576
	ds_write_b128 v247, v[148:151] offset:592
	ds_write_b128 v247, v[152:155] offset:608
	ds_write_b128 v247, v[156:159] offset:624
	s_mov_b64 exec, -1
	v_rcp_f32_e32 v220, v128
	v_rcp_f32_e32 v221, v129
	v_lshlrev_b32_e32 v218, 16, v48
	v_and_b32_e32 v219, 0xffff0000, v48
	v_pk_mul_f32 v[218:219], v[128:129], v[218:219]
	v_pk_mul_f32 v[220:221], v[220:221], v[96:97]
	v_cvt_pk_bf16_f32 v202, v218, v219
	v_cvt_pk_bf16_f32 v184, v220, v221
	v_rcp_f32_e32 v220, v130
	v_rcp_f32_e32 v221, v131
	v_lshlrev_b32_e32 v218, 16, v49
	v_and_b32_e32 v219, 0xffff0000, v49
	v_pk_mul_f32 v[218:219], v[130:131], v[218:219]
	v_pk_mul_f32 v[220:221], v[220:221], v[98:99]
	v_cvt_pk_bf16_f32 v203, v218, v219
	v_cvt_pk_bf16_f32 v185, v220, v221
	v_rcp_f32_e32 v220, v132
	v_rcp_f32_e32 v221, v133
	v_lshlrev_b32_e32 v218, 16, v50
	v_and_b32_e32 v219, 0xffff0000, v50
	v_pk_mul_f32 v[218:219], v[132:133], v[218:219]
	v_pk_mul_f32 v[220:221], v[220:221], v[100:101]
	v_cvt_pk_bf16_f32 v204, v218, v219
	v_cvt_pk_bf16_f32 v186, v220, v221
	v_rcp_f32_e32 v220, v134
	v_rcp_f32_e32 v221, v135
	v_lshlrev_b32_e32 v218, 16, v51
	v_and_b32_e32 v219, 0xffff0000, v51
	v_pk_mul_f32 v[218:219], v[134:135], v[218:219]
	v_pk_mul_f32 v[220:221], v[220:221], v[102:103]
	v_cvt_pk_bf16_f32 v205, v218, v219
	v_cvt_pk_bf16_f32 v187, v220, v221
	global_load_dwordx4 v[48:51], v228, s[30:31]
	v_rcp_f32_e32 v220, v136
	v_rcp_f32_e32 v221, v137
	v_lshlrev_b32_e32 v218, 16, v52
	v_and_b32_e32 v219, 0xffff0000, v52
	v_pk_mul_f32 v[218:219], v[136:137], v[218:219]
	v_pk_mul_f32 v[220:221], v[220:221], v[104:105]
	v_cvt_pk_bf16_f32 v206, v218, v219
	v_cvt_pk_bf16_f32 v188, v220, v221
	v_rcp_f32_e32 v220, v138
	v_rcp_f32_e32 v221, v139
	v_lshlrev_b32_e32 v218, 16, v53
	v_and_b32_e32 v219, 0xffff0000, v53
	v_pk_mul_f32 v[218:219], v[138:139], v[218:219]
	v_pk_mul_f32 v[220:221], v[220:221], v[106:107]
	v_cvt_pk_bf16_f32 v207, v218, v219
	v_cvt_pk_bf16_f32 v189, v220, v221
	v_rcp_f32_e32 v220, v140
	v_rcp_f32_e32 v221, v141
	v_lshlrev_b32_e32 v218, 16, v54
	v_and_b32_e32 v219, 0xffff0000, v54
	v_pk_mul_f32 v[218:219], v[140:141], v[218:219]
	v_pk_mul_f32 v[220:221], v[220:221], v[108:109]
	v_cvt_pk_bf16_f32 v208, v218, v219
	v_cvt_pk_bf16_f32 v190, v220, v221
	v_rcp_f32_e32 v220, v142
	v_rcp_f32_e32 v221, v143
	v_lshlrev_b32_e32 v218, 16, v55
	v_and_b32_e32 v219, 0xffff0000, v55
	v_pk_mul_f32 v[218:219], v[142:143], v[218:219]
	v_pk_mul_f32 v[220:221], v[220:221], v[110:111]
	v_cvt_pk_bf16_f32 v209, v218, v219
	v_cvt_pk_bf16_f32 v191, v220, v221
	global_load_dwordx4 v[52:55], v228, s[30:31] offset:16
	v_rcp_f32_e32 v220, v144
	v_rcp_f32_e32 v221, v145
	v_lshlrev_b32_e32 v218, 16, v56
	v_and_b32_e32 v219, 0xffff0000, v56
	v_pk_mul_f32 v[218:219], v[144:145], v[218:219]
	v_pk_mul_f32 v[220:221], v[220:221], v[112:113]
	v_cvt_pk_bf16_f32 v210, v218, v219
	v_cvt_pk_bf16_f32 v192, v220, v221
	v_rcp_f32_e32 v220, v146
	v_rcp_f32_e32 v221, v147
	v_lshlrev_b32_e32 v218, 16, v57
	v_and_b32_e32 v219, 0xffff0000, v57
	v_pk_mul_f32 v[218:219], v[146:147], v[218:219]
	v_pk_mul_f32 v[220:221], v[220:221], v[114:115]
	v_cvt_pk_bf16_f32 v211, v218, v219
	v_cvt_pk_bf16_f32 v193, v220, v221
	v_rcp_f32_e32 v220, v148
	v_rcp_f32_e32 v221, v149
	v_lshlrev_b32_e32 v218, 16, v58
	v_and_b32_e32 v219, 0xffff0000, v58
	v_pk_mul_f32 v[218:219], v[148:149], v[218:219]
	v_pk_mul_f32 v[220:221], v[220:221], v[116:117]
	v_cvt_pk_bf16_f32 v212, v218, v219
	v_cvt_pk_bf16_f32 v194, v220, v221
	v_rcp_f32_e32 v220, v150
	v_rcp_f32_e32 v221, v151
	v_lshlrev_b32_e32 v218, 16, v59
	v_and_b32_e32 v219, 0xffff0000, v59
	v_pk_mul_f32 v[218:219], v[150:151], v[218:219]
	v_pk_mul_f32 v[220:221], v[220:221], v[118:119]
	v_cvt_pk_bf16_f32 v213, v218, v219
	v_cvt_pk_bf16_f32 v195, v220, v221
	global_load_dwordx4 v[56:59], v228, s[30:31] offset:32
	v_rcp_f32_e32 v220, v152
	v_rcp_f32_e32 v221, v153
	v_lshlrev_b32_e32 v218, 16, v60
	v_and_b32_e32 v219, 0xffff0000, v60
	v_pk_mul_f32 v[218:219], v[152:153], v[218:219]
	v_pk_mul_f32 v[220:221], v[220:221], v[120:121]
	v_cvt_pk_bf16_f32 v214, v218, v219
	v_cvt_pk_bf16_f32 v196, v220, v221
	v_rcp_f32_e32 v220, v154
	v_rcp_f32_e32 v221, v155
	v_lshlrev_b32_e32 v218, 16, v61
	v_and_b32_e32 v219, 0xffff0000, v61
	v_pk_mul_f32 v[218:219], v[154:155], v[218:219]
	v_pk_mul_f32 v[220:221], v[220:221], v[122:123]
	v_cvt_pk_bf16_f32 v215, v218, v219
	v_cvt_pk_bf16_f32 v197, v220, v221
	v_rcp_f32_e32 v220, v156
	v_rcp_f32_e32 v221, v157
	v_lshlrev_b32_e32 v218, 16, v62
	v_and_b32_e32 v219, 0xffff0000, v62
	v_pk_mul_f32 v[218:219], v[156:157], v[218:219]
	v_pk_mul_f32 v[220:221], v[220:221], v[124:125]
	v_cvt_pk_bf16_f32 v216, v218, v219
	v_cvt_pk_bf16_f32 v198, v220, v221
	v_rcp_f32_e32 v220, v158
	v_rcp_f32_e32 v221, v159
	v_lshlrev_b32_e32 v218, 16, v63
	v_and_b32_e32 v219, 0xffff0000, v63
	v_pk_mul_f32 v[218:219], v[158:159], v[218:219]
	v_pk_mul_f32 v[220:221], v[220:221], v[126:127]
	v_cvt_pk_bf16_f32 v217, v218, v219
	v_cvt_pk_bf16_f32 v199, v220, v221
	global_load_dwordx4 v[60:63], v228, s[30:31] offset:48
	v_add_u32_e32 v228, s76, v228
	ds_write_b128 v222, v[184:187] offset:17408
	ds_write_b128 v223, v[188:191] offset:17408
	ds_write_b128 v224, v[192:195] offset:17408
	ds_write_b128 v225, v[196:199] offset:17408
	ds_write_b128 v227, v[202:205]
	ds_write_b128 v227, v[206:209] offset:16
	ds_write_b128 v227, v[210:213] offset:32
	ds_write_b128 v227, v[214:217] offset:48
	s_waitcnt lgkmcnt(0)
	s_barrier
	s_add_u32 s70, s70, 1
	s_cmp_lt_u32 s70, 32
	s_cbranch_scc1 .Lh2_prep_loop
	s_waitcnt vmcnt(0)
	s_barrier
	s_branch .Lh2_done

.Lh2_mfma_loop:
	ds_read_b128 v[64:67], v247
	ds_read_b128 v[144:147], v226 offset:1024
	ds_read_b128 v[68:71], v247 offset:32
	ds_read_b128 v[148:151], v227 offset:1024
	ds_read_b128 v[72:75], v247 offset:64
	ds_read_b128 v[152:155], v228 offset:1024
	ds_read_b128 v[76:79], v247 offset:96
	ds_read_b128 v[156:159], v229 offset:1024
	ds_read_b128 v[80:83], v247 offset:128
	ds_read_b128 v[184:187], v230 offset:1024
	ds_read_b128 v[84:87], v247 offset:160
	ds_read_b128 v[188:191], v231 offset:1024
	s_waitcnt lgkmcnt(10)
	v_mfma_f32_32x32x16_bf16 v[96:111], v[144:147], v[64:67], 0
	ds_read_b128 v[88:91], v247 offset:192
	ds_read_b128 v[192:195], v232 offset:1024
	s_waitcnt lgkmcnt(10)
	v_mfma_f32_32x32x16_bf16 v[96:111], v[148:151], v[68:71], v[96:111]
	ds_read_b128 v[92:95], v247 offset:224
	ds_read_b128 v[196:199], v233 offset:1024
	s_waitcnt lgkmcnt(10)
	v_mfma_f32_32x32x16_bf16 v[96:111], v[152:155], v[72:75], v[96:111]
	ds_read_b64_tr_b16 v[202:203], v244 offset:0
	ds_read_b64_tr_b16 v[204:205], v245 offset:0
	s_waitcnt lgkmcnt(10)
	v_mfma_f32_32x32x16_bf16 v[96:111], v[156:159], v[76:79], v[96:111]
	ds_read_b64_tr_b16 v[206:207], v244 offset:4096
	ds_read_b64_tr_b16 v[208:209], v245 offset:4096
	s_waitcnt lgkmcnt(10)
	v_mfma_f32_32x32x16_bf16 v[96:111], v[184:187], v[80:83], v[96:111]
	ds_read2_b64 v[210:213], v251 offset0:0 offset1:2
	ds_read2_b64 v[214:217], v251 offset0:4 offset1:6
	s_waitcnt lgkmcnt(10)
	v_mfma_f32_32x32x16_bf16 v[96:111], v[188:191], v[84:87], v[96:111]
	ds_read2_b64 v[144:147], v251 offset0:8 offset1:10
	ds_read2_b64 v[148:151], v251 offset0:12 offset1:14
	s_waitcnt lgkmcnt(10)
	v_mfma_f32_32x32x16_bf16 v[96:111], v[192:195], v[88:91], v[96:111]
	ds_read2_b64 v[152:155], v251 offset0:16 offset1:18
	ds_read2_b64 v[156:159], v251 offset0:20 offset1:22
	s_waitcnt lgkmcnt(10)
	v_mfma_f32_32x32x16_bf16 v[96:111], v[196:199], v[92:95], v[96:111]
	ds_read2_b64 v[184:187], v251 offset0:24 offset1:26
	ds_read2_b64 v[188:191], v251 offset0:28 offset1:30
	s_waitcnt lgkmcnt(10)
	s_nop 8
	v_cndmask_b32_e64 v96, v96, 0, s[38:39]
	v_cndmask_b32_e64 v97, v97, 0, s[40:41]
	v_cndmask_b32_e64 v98, v98, 0, s[42:43]
	v_cndmask_b32_e64 v99, v99, 0, s[44:45]
	v_cndmask_b32_e64 v100, v100, 0, s[46:47]
	v_cndmask_b32_e64 v101, v101, 0, s[48:49]
	v_cndmask_b32_e64 v102, v102, 0, s[50:51]
	v_cndmask_b32_e64 v103, v103, 0, s[52:53]
	v_cndmask_b32_e64 v104, v104, 0, s[54:55]
	v_cndmask_b32_e64 v105, v105, 0, s[56:57]
	v_cndmask_b32_e64 v106, v106, 0, s[58:59]
	v_cndmask_b32_e64 v107, v107, 0, s[60:61]
	v_cndmask_b32_e64 v108, v108, 0, s[62:63]
	v_cndmask_b32_e64 v109, v109, 0, s[64:65]
	v_cndmask_b32_e64 v110, v110, 0, s[66:67]
	v_cndmask_b32_e64 v111, v111, 0, s[68:69]
	v_cvt_pk_bf16_f32 v96, v96, v97
	v_cvt_pk_bf16_f32 v97, v98, v99
	v_cvt_pk_bf16_f32 v98, v100, v101
	v_cvt_pk_bf16_f32 v99, v102, v103
	v_cvt_pk_bf16_f32 v100, v104, v105
	v_cvt_pk_bf16_f32 v101, v106, v107
	v_cvt_pk_bf16_f32 v102, v108, v109
	v_cvt_pk_bf16_f32 v103, v110, v111
	v_mfma_f32_32x32x16_bf16 v[128:143], v[202:205], v[96:99], 0
	s_waitcnt lgkmcnt(8)
	v_mfma_f32_32x32x16_bf16 v[128:143], v[206:209], v[100:103], v[128:143]
	v_cvt_pk_bf16_f32 v218, v0, v1
	v_cvt_pk_bf16_f32 v219, v2, v3
	v_cvt_pk_bf16_f32 v220, v4, v5
	v_cvt_pk_bf16_f32 v221, v6, v7
	s_waitcnt lgkmcnt(7)
	s_nop 1
	v_mfma_f32_32x32x16_bf16 v[128:143], v[218:221], v[210:213], v[128:143]
	v_cvt_pk_bf16_f32 v222, v8, v9
	v_cvt_pk_bf16_f32 v223, v10, v11
	v_cvt_pk_bf16_f32 v224, v12, v13
	v_cvt_pk_bf16_f32 v225, v14, v15
	s_waitcnt lgkmcnt(6)
	s_nop 1
	v_mfma_f32_32x32x16_bf16 v[128:143], v[222:225], v[214:217], v[128:143]
	v_cvt_pk_bf16_f32 v218, v16, v17
	v_cvt_pk_bf16_f32 v219, v18, v19
	v_cvt_pk_bf16_f32 v220, v20, v21
	v_cvt_pk_bf16_f32 v221, v22, v23
	s_waitcnt lgkmcnt(5)
	s_nop 1
	v_mfma_f32_32x32x16_bf16 v[128:143], v[218:221], v[144:147], v[128:143]
	v_cvt_pk_bf16_f32 v222, v24, v25
	v_cvt_pk_bf16_f32 v223, v26, v27
	v_cvt_pk_bf16_f32 v224, v28, v29
	v_cvt_pk_bf16_f32 v225, v30, v31
	s_waitcnt lgkmcnt(4)
	s_nop 1
	v_mfma_f32_32x32x16_bf16 v[128:143], v[222:225], v[148:151], v[128:143]
	v_cvt_pk_bf16_f32 v218, v32, v33
	v_cvt_pk_bf16_f32 v219, v34, v35
	v_cvt_pk_bf16_f32 v220, v36, v37
	v_cvt_pk_bf16_f32 v221, v38, v39
	s_waitcnt lgkmcnt(3)
	s_nop 1
	v_mfma_f32_32x32x16_bf16 v[128:143], v[218:221], v[152:155], v[128:143]
	v_cvt_pk_bf16_f32 v222, v40, v41
	v_cvt_pk_bf16_f32 v223, v42, v43
	v_cvt_pk_bf16_f32 v224, v44, v45
	v_cvt_pk_bf16_f32 v225, v46, v47
	s_waitcnt lgkmcnt(2)
	s_nop 1
	v_mfma_f32_32x32x16_bf16 v[128:143], v[222:225], v[156:159], v[128:143]
	v_cvt_pk_bf16_f32 v218, v48, v49
	v_cvt_pk_bf16_f32 v219, v50, v51
	v_cvt_pk_bf16_f32 v220, v52, v53
	v_cvt_pk_bf16_f32 v221, v54, v55
	s_waitcnt lgkmcnt(1)
	s_nop 1
	v_mfma_f32_32x32x16_bf16 v[128:143], v[218:221], v[184:187], v[128:143]
	v_cvt_pk_bf16_f32 v222, v56, v57
	v_cvt_pk_bf16_f32 v223, v58, v59
	v_cvt_pk_bf16_f32 v224, v60, v61
	v_cvt_pk_bf16_f32 v225, v62, v63
	s_waitcnt lgkmcnt(0)
	s_nop 1
	v_mfma_f32_32x32x16_bf16 v[128:143], v[222:225], v[188:191], v[128:143]
	ds_read_b128 v[64:67], v249
	ds_read_b128 v[192:195], v226 offset:1024
	ds_read_b128 v[68:71], v249 offset:32
	ds_read_b128 v[196:199], v227 offset:1024
	ds_read_b128 v[72:75], v249 offset:64
	ds_read_b128 v[202:205], v228 offset:1024
	ds_read_b128 v[76:79], v249 offset:96
	ds_read_b128 v[206:209], v229 offset:1024
	ds_read_b128 v[80:83], v249 offset:128
	ds_read_b128 v[210:213], v230 offset:1024
	ds_read_b128 v[84:87], v249 offset:160
	ds_read_b128 v[214:217], v231 offset:1024
	s_waitcnt lgkmcnt(11)
	v_cvt_pk_bf16_f32 v218, v128, v129
	v_cvt_pk_bf16_f32 v219, v130, v131
	v_cvt_pk_bf16_f32 v220, v132, v133
	v_cvt_pk_bf16_f32 v221, v134, v135
	v_cvt_pk_bf16_f32 v222, v136, v137
	v_cvt_pk_bf16_f32 v223, v138, v139
	v_cvt_pk_bf16_f32 v224, v140, v141
	v_cvt_pk_bf16_f32 v225, v142, v143
	ds_write2_b64 v168, v[218:219], v[220:221] offset1:2
	ds_write2_b64 v168, v[222:223], v[224:225] offset0:4 offset1:6
	ds_read_b128 v[218:221], v169
	ds_read_b128 v[222:225], v170
	v_add_u32_e32 v183, s71, v171
	v_add_u32_e32 v201, s72, v171
	s_waitcnt lgkmcnt(0)
	global_store_dwordx4 v183, v[218:221], s[14:15]
	global_store_dwordx4 v201, v[222:225], s[14:15]
	ds_read_b128 v[88:91], v249 offset:192
	ds_read_b128 v[144:147], v232 offset:1024
	ds_read_b128 v[92:95], v249 offset:224
	ds_read_b128 v[148:151], v233 offset:1024
	ds_read_b128 v[152:155], v226 offset:9216
	ds_read_b128 v[156:159], v227 offset:9216
	ds_read_b128 v[184:187], v228 offset:9216
	ds_read_b128 v[188:191], v229 offset:9216
	v_mfma_f32_32x32x16_bf16 v[96:111], v[192:195], v[64:67], 0
	ds_read_b128 v[192:195], v230 offset:9216
	v_mfma_f32_32x32x16_bf16 v[96:111], v[196:199], v[68:71], v[96:111]
	ds_read_b128 v[196:199], v231 offset:9216
	v_mfma_f32_32x32x16_bf16 v[96:111], v[202:205], v[72:75], v[96:111]
	ds_read_b128 v[202:205], v232 offset:9216
	v_mfma_f32_32x32x16_bf16 v[96:111], v[206:209], v[76:79], v[96:111]
	ds_read_b128 v[206:209], v233 offset:9216
	v_mfma_f32_32x32x16_bf16 v[96:111], v[210:213], v[80:83], v[96:111]
	v_mfma_f32_32x32x16_bf16 v[96:111], v[214:217], v[84:87], v[96:111]
	s_waitcnt lgkmcnt(10)
	v_mfma_f32_32x32x16_bf16 v[96:111], v[144:147], v[88:91], v[96:111]
	ds_read_b64_tr_b16 v[210:211], v244 offset:0
	ds_read_b64_tr_b16 v[212:213], v245 offset:0
	s_waitcnt lgkmcnt(10)
	v_mfma_f32_32x32x16_bf16 v[96:111], v[148:151], v[92:95], v[96:111]
	ds_read_b64_tr_b16 v[214:215], v244 offset:4096
	ds_read_b64_tr_b16 v[216:217], v245 offset:4096
	s_waitcnt lgkmcnt(11)
	v_mfma_f32_32x32x16_bf16 v[112:127], v[152:155], v[64:67], 0
	s_waitcnt lgkmcnt(10)
	v_mfma_f32_32x32x16_bf16 v[112:127], v[156:159], v[68:71], v[112:127]
	ds_read_b64_tr_b16 v[144:145], v244 offset:8192
	ds_read_b64_tr_b16 v[146:147], v245 offset:8192
	s_waitcnt lgkmcnt(11)
	v_mfma_f32_32x32x16_bf16 v[112:127], v[184:187], v[72:75], v[112:127]
	s_waitcnt lgkmcnt(10)
	v_mfma_f32_32x32x16_bf16 v[112:127], v[188:191], v[76:79], v[112:127]
	ds_read_b64_tr_b16 v[148:149], v244 offset:12288
	ds_read_b64_tr_b16 v[150:151], v245 offset:12288
	s_waitcnt lgkmcnt(11)
	v_mfma_f32_32x32x16_bf16 v[112:127], v[192:195], v[80:83], v[112:127]
	ds_read2_b64 v[152:155], v253 offset0:0 offset1:2
	s_waitcnt lgkmcnt(11)
	v_mfma_f32_32x32x16_bf16 v[112:127], v[196:199], v[84:87], v[112:127]
	ds_read2_b64 v[156:159], v253 offset0:4 offset1:6
	s_waitcnt lgkmcnt(11)
	v_mfma_f32_32x32x16_bf16 v[112:127], v[202:205], v[88:91], v[112:127]
	ds_read2_b64 v[184:187], v253 offset0:8 offset1:10
	s_waitcnt lgkmcnt(11)
	v_mfma_f32_32x32x16_bf16 v[112:127], v[206:209], v[92:95], v[112:127]
	ds_read2_b64 v[188:191], v253 offset0:12 offset1:14
	s_waitcnt lgkmcnt(10)
	v_cvt_pk_bf16_f32 v96, v96, v97
	v_cvt_pk_bf16_f32 v97, v98, v99
	v_cvt_pk_bf16_f32 v98, v100, v101
	v_cvt_pk_bf16_f32 v99, v102, v103
	v_cvt_pk_bf16_f32 v100, v104, v105
	v_cvt_pk_bf16_f32 v101, v106, v107
	v_cvt_pk_bf16_f32 v102, v108, v109
	v_cvt_pk_bf16_f32 v103, v110, v111
	s_nop 1
	v_cndmask_b32_e64 v112, v112, 0, s[38:39]
	v_cndmask_b32_e64 v113, v113, 0, s[40:41]
	v_cndmask_b32_e64 v114, v114, 0, s[42:43]
	v_cndmask_b32_e64 v115, v115, 0, s[44:45]
	v_cndmask_b32_e64 v116, v116, 0, s[46:47]
	v_cndmask_b32_e64 v117, v117, 0, s[48:49]
	v_cndmask_b32_e64 v118, v118, 0, s[50:51]
	v_cndmask_b32_e64 v119, v119, 0, s[52:53]
	v_cndmask_b32_e64 v120, v120, 0, s[54:55]
	v_cndmask_b32_e64 v121, v121, 0, s[56:57]
	v_cndmask_b32_e64 v122, v122, 0, s[58:59]
	v_cndmask_b32_e64 v123, v123, 0, s[60:61]
	v_cndmask_b32_e64 v124, v124, 0, s[62:63]
	v_cndmask_b32_e64 v125, v125, 0, s[64:65]
	v_cndmask_b32_e64 v126, v126, 0, s[66:67]
	v_cndmask_b32_e64 v127, v127, 0, s[68:69]
	v_cvt_pk_bf16_f32 v112, v112, v113
	v_cvt_pk_bf16_f32 v113, v114, v115
	v_cvt_pk_bf16_f32 v114, v116, v117
	v_cvt_pk_bf16_f32 v115, v118, v119
	v_cvt_pk_bf16_f32 v116, v120, v121
	v_cvt_pk_bf16_f32 v117, v122, v123
	v_cvt_pk_bf16_f32 v118, v124, v125
	v_cvt_pk_bf16_f32 v119, v126, v127
	ds_read2_b64 v[192:195], v253 offset0:16 offset1:18
	ds_read2_b64 v[196:199], v253 offset0:20 offset1:22
	v_mfma_f32_32x32x16_bf16 v[128:143], v[210:213], v[96:99], 0
	s_waitcnt lgkmcnt(10)
	v_mfma_f32_32x32x16_bf16 v[128:143], v[214:217], v[100:103], v[128:143]
	ds_read2_b64 v[202:205], v253 offset0:24 offset1:26
	ds_read2_b64 v[206:209], v253 offset0:28 offset1:30
	s_waitcnt lgkmcnt(10)
	v_mfma_f32_32x32x16_bf16 v[128:143], v[144:147], v[112:115], v[128:143]
	ds_read_b64_tr_b16 v[210:211], v242 offset:0
	ds_read_b64_tr_b16 v[212:213], v243 offset:0
	s_waitcnt lgkmcnt(10)
	v_mfma_f32_32x32x16_bf16 v[128:143], v[148:151], v[116:119], v[128:143]
	v_cvt_pk_bf16_f32 v218, v0, v1
	v_cvt_pk_bf16_f32 v219, v2, v3
	v_cvt_pk_bf16_f32 v220, v4, v5
	v_cvt_pk_bf16_f32 v221, v6, v7
	ds_read_b64_tr_b16 v[214:215], v234 offset:1024
	ds_read_b64_tr_b16 v[216:217], v235 offset:1024
	s_waitcnt lgkmcnt(11)
	s_nop 1
	v_mfma_f32_32x32x16_bf16 v[128:143], v[218:221], v[152:155], v[128:143]
	v_cvt_pk_bf16_f32 v222, v8, v9
	v_cvt_pk_bf16_f32 v223, v10, v11
	v_cvt_pk_bf16_f32 v224, v12, v13
	v_cvt_pk_bf16_f32 v225, v14, v15
	s_waitcnt lgkmcnt(10)
	s_nop 1
	v_mfma_f32_32x32x16_bf16 v[128:143], v[222:225], v[156:159], v[128:143]
	v_cvt_pk_bf16_f32 v218, v16, v17
	v_cvt_pk_bf16_f32 v219, v18, v19
	v_cvt_pk_bf16_f32 v220, v20, v21
	v_cvt_pk_bf16_f32 v221, v22, v23
	ds_read_b64_tr_b16 v[144:145], v236 offset:1024
	ds_read_b64_tr_b16 v[146:147], v237 offset:1024
	s_waitcnt lgkmcnt(11)
	s_nop 1
	v_mfma_f32_32x32x16_bf16 v[128:143], v[218:221], v[184:187], v[128:143]
	v_cvt_pk_bf16_f32 v222, v24, v25
	v_cvt_pk_bf16_f32 v223, v26, v27
	v_cvt_pk_bf16_f32 v224, v28, v29
	v_cvt_pk_bf16_f32 v225, v30, v31
	s_waitcnt lgkmcnt(10)
	s_nop 1
	v_mfma_f32_32x32x16_bf16 v[128:143], v[222:225], v[188:191], v[128:143]
	v_cvt_pk_bf16_f32 v218, v32, v33
	v_cvt_pk_bf16_f32 v219, v34, v35
	v_cvt_pk_bf16_f32 v220, v36, v37
	v_cvt_pk_bf16_f32 v221, v38, v39
	ds_read_b64_tr_b16 v[148:149], v238 offset:1024
	ds_read_b64_tr_b16 v[150:151], v239 offset:1024
	s_waitcnt lgkmcnt(11)
	s_nop 1
	v_mfma_f32_32x32x16_bf16 v[128:143], v[218:221], v[192:195], v[128:143]
	v_cvt_pk_bf16_f32 v222, v40, v41
	v_cvt_pk_bf16_f32 v223, v42, v43
	v_cvt_pk_bf16_f32 v224, v44, v45
	v_cvt_pk_bf16_f32 v225, v46, v47
	s_waitcnt lgkmcnt(10)
	s_nop 1
	v_mfma_f32_32x32x16_bf16 v[128:143], v[222:225], v[196:199], v[128:143]
	v_cvt_pk_bf16_f32 v218, v48, v49
	v_cvt_pk_bf16_f32 v219, v50, v51
	v_cvt_pk_bf16_f32 v220, v52, v53
	v_cvt_pk_bf16_f32 v221, v54, v55
	ds_read_b64_tr_b16 v[152:153], v240 offset:1024
	ds_read_b64_tr_b16 v[154:155], v241 offset:1024
	s_waitcnt lgkmcnt(11)
	s_nop 1
	v_mfma_f32_32x32x16_bf16 v[128:143], v[218:221], v[202:205], v[128:143]
	v_cvt_pk_bf16_f32 v222, v56, v57
	v_cvt_pk_bf16_f32 v223, v58, v59
	v_cvt_pk_bf16_f32 v224, v60, v61
	v_cvt_pk_bf16_f32 v225, v62, v63
	s_waitcnt lgkmcnt(10)
	s_nop 1
	v_mfma_f32_32x32x16_bf16 v[128:143], v[222:225], v[206:209], v[128:143]
	ds_read_b64_tr_b16 v[156:157], v242 offset:4096
	ds_read_b64_tr_b16 v[158:159], v243 offset:4096
	s_waitcnt lgkmcnt(10)
	s_nop 8
	v_cvt_pk_bf16_f32 v218, v128, v129
	v_cvt_pk_bf16_f32 v219, v130, v131
	v_cvt_pk_bf16_f32 v220, v132, v133
	v_cvt_pk_bf16_f32 v221, v134, v135
	v_cvt_pk_bf16_f32 v222, v136, v137
	v_cvt_pk_bf16_f32 v223, v138, v139
	v_cvt_pk_bf16_f32 v224, v140, v141
	v_cvt_pk_bf16_f32 v225, v142, v143
	ds_write2_b64 v168, v[218:219], v[220:221] offset1:2
	ds_write2_b64 v168, v[222:223], v[224:225] offset0:4 offset1:6
	ds_read_b128 v[218:221], v169
	ds_read_b128 v[222:225], v170
	v_add_u32_e32 v183, s73, v171
	v_add_u32_e32 v201, s75, v171
	s_waitcnt lgkmcnt(0)
	global_store_dwordx4 v183, v[218:221], s[14:15]
	global_store_dwordx4 v201, v[222:225], s[14:15]
	ds_read_b64_tr_b16 v[184:185], v234 offset:5120
	ds_read_b64_tr_b16 v[186:187], v235 offset:5120
	ds_read_b64_tr_b16 v[188:189], v236 offset:5120
	ds_read_b64_tr_b16 v[190:191], v237 offset:5120
	ds_read_b64_tr_b16 v[192:193], v238 offset:5120
	ds_read_b64_tr_b16 v[194:195], v239 offset:5120
	ds_read_b64_tr_b16 v[196:197], v240 offset:5120
	ds_read_b64_tr_b16 v[198:199], v241 offset:5120
	ds_read_b64_tr_b16 v[202:203], v242 offset:8192
	ds_read_b64_tr_b16 v[204:205], v243 offset:8192
	ds_read_b64_tr_b16 v[206:207], v234 offset:9216
	ds_read_b64_tr_b16 v[208:209], v235 offset:9216
	v_mfma_f32_32x32x16_bf16 v[0:15], v[214:217], v[210:213], v[0:15]
	v_mfma_f32_32x32x16_bf16 v[16:31], v[144:147], v[210:213], v[16:31]
	v_mfma_f32_32x32x16_bf16 v[32:47], v[148:151], v[210:213], v[32:47]
	v_mfma_f32_32x32x16_bf16 v[48:63], v[152:155], v[210:213], v[48:63]
	s_waitcnt lgkmcnt(10)
	v_mfma_f32_32x32x16_bf16 v[0:15], v[184:187], v[156:159], v[0:15]
	ds_read_b64_tr_b16 v[214:215], v236 offset:9216
	ds_read_b64_tr_b16 v[216:217], v237 offset:9216
	s_waitcnt lgkmcnt(10)
	v_mfma_f32_32x32x16_bf16 v[16:31], v[188:191], v[156:159], v[16:31]
	ds_read_b64_tr_b16 v[144:145], v238 offset:9216
	ds_read_b64_tr_b16 v[146:147], v239 offset:9216
	s_waitcnt lgkmcnt(10)
	v_mfma_f32_32x32x16_bf16 v[32:47], v[192:195], v[156:159], v[32:47]
	ds_read_b64_tr_b16 v[148:149], v240 offset:9216
	ds_read_b64_tr_b16 v[150:151], v241 offset:9216
	s_waitcnt lgkmcnt(10)
	v_mfma_f32_32x32x16_bf16 v[48:63], v[196:199], v[156:159], v[48:63]
	ds_read_b64_tr_b16 v[152:153], v242 offset:12288
	ds_read_b64_tr_b16 v[154:155], v243 offset:12288
	s_waitcnt lgkmcnt(8)
	v_mfma_f32_32x32x16_bf16 v[0:15], v[206:209], v[202:205], v[0:15]
	ds_read_b64_tr_b16 v[210:211], v234 offset:13312
	ds_read_b64_tr_b16 v[212:213], v235 offset:13312
	ds_read_b64_tr_b16 v[184:185], v236 offset:13312
	ds_read_b64_tr_b16 v[186:187], v237 offset:13312
	s_waitcnt lgkmcnt(10)
	v_mfma_f32_32x32x16_bf16 v[16:31], v[214:217], v[202:205], v[16:31]
	ds_read_b64_tr_b16 v[188:189], v238 offset:13312
	ds_read_b64_tr_b16 v[190:191], v239 offset:13312
	s_waitcnt lgkmcnt(10)
	v_mfma_f32_32x32x16_bf16 v[32:47], v[144:147], v[202:205], v[32:47]
	ds_read_b64_tr_b16 v[192:193], v240 offset:13312
	ds_read_b64_tr_b16 v[194:195], v241 offset:13312
	s_waitcnt lgkmcnt(10)
	v_mfma_f32_32x32x16_bf16 v[48:63], v[148:151], v[202:205], v[48:63]
	ds_read_b128 v[196:199], v255 offset:0
	ds_read_b128 v[156:159], v255 offset:32
	s_waitcnt lgkmcnt(8)
	v_mfma_f32_32x32x16_bf16 v[0:15], v[210:213], v[152:155], v[0:15]
	ds_read_b128 v[206:209], v255 offset:64
	ds_read_b128 v[214:217], v255 offset:96
	ds_read_b128 v[144:147], v255 offset:128
	ds_read_b128 v[148:151], v255 offset:160
	s_waitcnt lgkmcnt(10)
	v_mfma_f32_32x32x16_bf16 v[16:31], v[184:187], v[152:155], v[16:31]
	ds_read_b128 v[202:205], v255 offset:192
	ds_read_b128 v[210:213], v255 offset:224
	s_waitcnt lgkmcnt(10)
	v_mfma_f32_32x32x16_bf16 v[32:47], v[188:191], v[152:155], v[32:47]
	ds_read_b128 v[184:187], v255 offset:256
	ds_read_b128 v[188:191], v255 offset:288
	s_waitcnt lgkmcnt(10)
	v_mfma_f32_32x32x16_bf16 v[48:63], v[192:195], v[152:155], v[48:63]
	ds_read_b128 v[192:195], v255 offset:320
	ds_read_b128 v[152:155], v255 offset:352
	s_waitcnt lgkmcnt(11)
	v_pk_mul_f32 v[0:1], v[0:1], v[196:197]
	v_pk_mul_f32 v[2:3], v[2:3], v[198:199]
	ds_read_b128 v[196:199], v255 offset:384
	s_waitcnt lgkmcnt(11)
	v_pk_mul_f32 v[4:5], v[4:5], v[156:157]
	v_pk_mul_f32 v[6:7], v[6:7], v[158:159]
	ds_read_b128 v[156:159], v255 offset:416
	s_waitcnt lgkmcnt(11)
	v_pk_mul_f32 v[8:9], v[8:9], v[206:207]
	v_pk_mul_f32 v[10:11], v[10:11], v[208:209]
	ds_read_b128 v[206:209], v255 offset:448
	s_waitcnt lgkmcnt(11)
	v_pk_mul_f32 v[12:13], v[12:13], v[214:215]
	v_pk_mul_f32 v[14:15], v[14:15], v[216:217]
	ds_read_b128 v[214:217], v255 offset:480
	s_waitcnt lgkmcnt(11)
	v_pk_mul_f32 v[16:17], v[16:17], v[144:145]
	v_pk_mul_f32 v[18:19], v[18:19], v[146:147]
	s_waitcnt lgkmcnt(10)
	v_pk_mul_f32 v[20:21], v[20:21], v[148:149]
	v_pk_mul_f32 v[22:23], v[22:23], v[150:151]
	s_waitcnt lgkmcnt(9)
	v_pk_mul_f32 v[24:25], v[24:25], v[202:203]
	v_pk_mul_f32 v[26:27], v[26:27], v[204:205]
	s_waitcnt lgkmcnt(8)
	v_pk_mul_f32 v[28:29], v[28:29], v[210:211]
	v_pk_mul_f32 v[30:31], v[30:31], v[212:213]
	s_waitcnt lgkmcnt(7)
	v_pk_mul_f32 v[32:33], v[32:33], v[184:185]
	v_pk_mul_f32 v[34:35], v[34:35], v[186:187]
	s_waitcnt lgkmcnt(6)
	v_pk_mul_f32 v[36:37], v[36:37], v[188:189]
	v_pk_mul_f32 v[38:39], v[38:39], v[190:191]
	s_waitcnt lgkmcnt(5)
	v_pk_mul_f32 v[40:41], v[40:41], v[192:193]
	v_pk_mul_f32 v[42:43], v[42:43], v[194:195]
	s_waitcnt lgkmcnt(4)
	v_pk_mul_f32 v[44:45], v[44:45], v[152:153]
	v_pk_mul_f32 v[46:47], v[46:47], v[154:155]
	s_waitcnt lgkmcnt(3)
	v_pk_mul_f32 v[48:49], v[48:49], v[196:197]
	v_pk_mul_f32 v[50:51], v[50:51], v[198:199]
	s_waitcnt lgkmcnt(2)
	v_pk_mul_f32 v[52:53], v[52:53], v[156:157]
	v_pk_mul_f32 v[54:55], v[54:55], v[158:159]
	s_waitcnt lgkmcnt(1)
	v_pk_mul_f32 v[56:57], v[56:57], v[206:207]
	v_pk_mul_f32 v[58:59], v[58:59], v[208:209]
	s_waitcnt lgkmcnt(0)
	v_pk_mul_f32 v[60:61], v[60:61], v[214:215]
	v_pk_mul_f32 v[62:63], v[62:63], v[216:217]
	v_add_u32_e32 v171, s33, v171
	s_mov_b32 s77, s76
	s_add_u32 s76, s76, 0x4000
	s_cmp_eq_u32 s76, 0x10400
	s_cselect_b32 s76, 0x1b400, s76
	s_cmp_eq_u32 s76, 0x23400
	s_cselect_b32 s76, 0x8400, s76
	s_sub_u32 s77, s76, s77
	v_add_u32_e32 v244, s77, v244
	v_add_u32_e32 v245, s77, v245
	v_add_u32_e32 v242, s77, v242
	v_add_u32_e32 v243, s77, v243
	s_barrier
	ds_read_b128 v[64:67], v248
	ds_read_b128 v[144:147], v226 offset:17408
	ds_read_b128 v[68:71], v248 offset:32
	ds_read_b128 v[148:151], v227 offset:17408
	ds_read_b128 v[72:75], v248 offset:64
	ds_read_b128 v[152:155], v228 offset:17408
	ds_read_b128 v[76:79], v248 offset:96
	ds_read_b128 v[156:159], v229 offset:17408
	ds_read_b128 v[80:83], v248 offset:128
	ds_read_b128 v[184:187], v230 offset:17408
	ds_read_b128 v[84:87], v248 offset:160
	ds_read_b128 v[188:191], v231 offset:17408
	s_waitcnt lgkmcnt(10)
	v_mfma_f32_32x32x16_bf16 v[96:111], v[144:147], v[64:67], 0
	ds_read_b128 v[88:91], v248 offset:192
	ds_read_b128 v[192:195], v232 offset:17408
	s_waitcnt lgkmcnt(10)
	v_mfma_f32_32x32x16_bf16 v[96:111], v[148:151], v[68:71], v[96:111]
	ds_read_b128 v[92:95], v248 offset:224
	ds_read_b128 v[196:199], v233 offset:17408
	s_waitcnt lgkmcnt(10)
	v_mfma_f32_32x32x16_bf16 v[96:111], v[152:155], v[72:75], v[96:111]
	ds_read_b64_tr_b16 v[202:203], v244 offset:0
	ds_read_b64_tr_b16 v[204:205], v245 offset:0
	s_waitcnt lgkmcnt(10)
	v_mfma_f32_32x32x16_bf16 v[96:111], v[156:159], v[76:79], v[96:111]
	ds_read_b64_tr_b16 v[206:207], v244 offset:4096
	ds_read_b64_tr_b16 v[208:209], v245 offset:4096
	s_waitcnt lgkmcnt(10)
	v_mfma_f32_32x32x16_bf16 v[96:111], v[184:187], v[80:83], v[96:111]
	ds_read2_b64 v[210:213], v252 offset0:0 offset1:2
	ds_read2_b64 v[214:217], v252 offset0:4 offset1:6
	s_waitcnt lgkmcnt(10)
	v_mfma_f32_32x32x16_bf16 v[96:111], v[188:191], v[84:87], v[96:111]
	ds_read2_b64 v[144:147], v252 offset0:8 offset1:10
	ds_read2_b64 v[148:151], v252 offset0:12 offset1:14
	s_waitcnt lgkmcnt(10)
	v_mfma_f32_32x32x16_bf16 v[96:111], v[192:195], v[88:91], v[96:111]
	ds_read2_b64 v[152:155], v252 offset0:16 offset1:18
	ds_read2_b64 v[156:159], v252 offset0:20 offset1:22
	s_waitcnt lgkmcnt(10)
	v_mfma_f32_32x32x16_bf16 v[96:111], v[196:199], v[92:95], v[96:111]
	ds_read2_b64 v[184:187], v252 offset0:24 offset1:26
	ds_read2_b64 v[188:191], v252 offset0:28 offset1:30
	s_waitcnt lgkmcnt(10)
	s_nop 8
	v_cndmask_b32_e64 v96, v96, 0, s[38:39]
	v_cndmask_b32_e64 v97, v97, 0, s[40:41]
	v_cndmask_b32_e64 v98, v98, 0, s[42:43]
	v_cndmask_b32_e64 v99, v99, 0, s[44:45]
	v_cndmask_b32_e64 v100, v100, 0, s[46:47]
	v_cndmask_b32_e64 v101, v101, 0, s[48:49]
	v_cndmask_b32_e64 v102, v102, 0, s[50:51]
	v_cndmask_b32_e64 v103, v103, 0, s[52:53]
	v_cndmask_b32_e64 v104, v104, 0, s[54:55]
	v_cndmask_b32_e64 v105, v105, 0, s[56:57]
	v_cndmask_b32_e64 v106, v106, 0, s[58:59]
	v_cndmask_b32_e64 v107, v107, 0, s[60:61]
	v_cndmask_b32_e64 v108, v108, 0, s[62:63]
	v_cndmask_b32_e64 v109, v109, 0, s[64:65]
	v_cndmask_b32_e64 v110, v110, 0, s[66:67]
	v_cndmask_b32_e64 v111, v111, 0, s[68:69]
	v_cvt_pk_bf16_f32 v96, v96, v97
	v_cvt_pk_bf16_f32 v97, v98, v99
	v_cvt_pk_bf16_f32 v98, v100, v101
	v_cvt_pk_bf16_f32 v99, v102, v103
	v_cvt_pk_bf16_f32 v100, v104, v105
	v_cvt_pk_bf16_f32 v101, v106, v107
	v_cvt_pk_bf16_f32 v102, v108, v109
	v_cvt_pk_bf16_f32 v103, v110, v111
	v_mfma_f32_32x32x16_bf16 v[128:143], v[202:205], v[96:99], 0
	s_waitcnt lgkmcnt(8)
	v_mfma_f32_32x32x16_bf16 v[128:143], v[206:209], v[100:103], v[128:143]
	v_cvt_pk_bf16_f32 v218, v0, v1
	v_cvt_pk_bf16_f32 v219, v2, v3
	v_cvt_pk_bf16_f32 v220, v4, v5
	v_cvt_pk_bf16_f32 v221, v6, v7
	s_waitcnt lgkmcnt(7)
	s_nop 1
	v_mfma_f32_32x32x16_bf16 v[128:143], v[218:221], v[210:213], v[128:143]
	v_cvt_pk_bf16_f32 v222, v8, v9
	v_cvt_pk_bf16_f32 v223, v10, v11
	v_cvt_pk_bf16_f32 v224, v12, v13
	v_cvt_pk_bf16_f32 v225, v14, v15
	s_waitcnt lgkmcnt(6)
	s_nop 1
	v_mfma_f32_32x32x16_bf16 v[128:143], v[222:225], v[214:217], v[128:143]
	v_cvt_pk_bf16_f32 v218, v16, v17
	v_cvt_pk_bf16_f32 v219, v18, v19
	v_cvt_pk_bf16_f32 v220, v20, v21
	v_cvt_pk_bf16_f32 v221, v22, v23
	s_waitcnt lgkmcnt(5)
	s_nop 1
	v_mfma_f32_32x32x16_bf16 v[128:143], v[218:221], v[144:147], v[128:143]
	v_cvt_pk_bf16_f32 v222, v24, v25
	v_cvt_pk_bf16_f32 v223, v26, v27
	v_cvt_pk_bf16_f32 v224, v28, v29
	v_cvt_pk_bf16_f32 v225, v30, v31
	s_waitcnt lgkmcnt(4)
	s_nop 1
	v_mfma_f32_32x32x16_bf16 v[128:143], v[222:225], v[148:151], v[128:143]
	v_cvt_pk_bf16_f32 v218, v32, v33
	v_cvt_pk_bf16_f32 v219, v34, v35
	v_cvt_pk_bf16_f32 v220, v36, v37
	v_cvt_pk_bf16_f32 v221, v38, v39
	s_waitcnt lgkmcnt(3)
	s_nop 1
	v_mfma_f32_32x32x16_bf16 v[128:143], v[218:221], v[152:155], v[128:143]
	v_cvt_pk_bf16_f32 v222, v40, v41
	v_cvt_pk_bf16_f32 v223, v42, v43
	v_cvt_pk_bf16_f32 v224, v44, v45
	v_cvt_pk_bf16_f32 v225, v46, v47
	s_waitcnt lgkmcnt(2)
	s_nop 1
	v_mfma_f32_32x32x16_bf16 v[128:143], v[222:225], v[156:159], v[128:143]
	v_cvt_pk_bf16_f32 v218, v48, v49
	v_cvt_pk_bf16_f32 v219, v50, v51
	v_cvt_pk_bf16_f32 v220, v52, v53
	v_cvt_pk_bf16_f32 v221, v54, v55
	s_waitcnt lgkmcnt(1)
	s_nop 1
	v_mfma_f32_32x32x16_bf16 v[128:143], v[218:221], v[184:187], v[128:143]
	v_cvt_pk_bf16_f32 v222, v56, v57
	v_cvt_pk_bf16_f32 v223, v58, v59
	v_cvt_pk_bf16_f32 v224, v60, v61
	v_cvt_pk_bf16_f32 v225, v62, v63
	s_waitcnt lgkmcnt(0)
	s_nop 1
	v_mfma_f32_32x32x16_bf16 v[128:143], v[222:225], v[188:191], v[128:143]
	ds_read_b128 v[64:67], v250
	ds_read_b128 v[192:195], v226 offset:17408
	ds_read_b128 v[68:71], v250 offset:32
	ds_read_b128 v[196:199], v227 offset:17408
	ds_read_b128 v[72:75], v250 offset:64
	ds_read_b128 v[202:205], v228 offset:17408
	ds_read_b128 v[76:79], v250 offset:96
	ds_read_b128 v[206:209], v229 offset:17408
	ds_read_b128 v[80:83], v250 offset:128
	ds_read_b128 v[210:213], v230 offset:17408
	ds_read_b128 v[84:87], v250 offset:160
	ds_read_b128 v[214:217], v231 offset:17408
	s_waitcnt lgkmcnt(11)
	v_cvt_pk_bf16_f32 v218, v128, v129
	v_cvt_pk_bf16_f32 v219, v130, v131
	v_cvt_pk_bf16_f32 v220, v132, v133
	v_cvt_pk_bf16_f32 v221, v134, v135
	v_cvt_pk_bf16_f32 v222, v136, v137
	v_cvt_pk_bf16_f32 v223, v138, v139
	v_cvt_pk_bf16_f32 v224, v140, v141
	v_cvt_pk_bf16_f32 v225, v142, v143
	ds_write2_b64 v168, v[218:219], v[220:221] offset1:2
	ds_write2_b64 v168, v[222:223], v[224:225] offset0:4 offset1:6
	ds_read_b128 v[218:221], v169
	ds_read_b128 v[222:225], v170
	v_add_u32_e32 v183, s71, v171
	v_add_u32_e32 v201, s72, v171
	s_waitcnt lgkmcnt(0)
	global_store_dwordx4 v183, v[218:221], s[14:15]
	global_store_dwordx4 v201, v[222:225], s[14:15]
	ds_read_b128 v[88:91], v250 offset:192
	ds_read_b128 v[144:147], v232 offset:17408
	ds_read_b128 v[92:95], v250 offset:224
	ds_read_b128 v[148:151], v233 offset:17408
	ds_read_b128 v[152:155], v226 offset:25600
	ds_read_b128 v[156:159], v227 offset:25600
	ds_read_b128 v[184:187], v228 offset:25600
	ds_read_b128 v[188:191], v229 offset:25600
	v_mfma_f32_32x32x16_bf16 v[96:111], v[192:195], v[64:67], 0
	ds_read_b128 v[192:195], v230 offset:25600
	v_mfma_f32_32x32x16_bf16 v[96:111], v[196:199], v[68:71], v[96:111]
	ds_read_b128 v[196:199], v231 offset:25600
	v_mfma_f32_32x32x16_bf16 v[96:111], v[202:205], v[72:75], v[96:111]
	ds_read_b128 v[202:205], v232 offset:25600
	v_mfma_f32_32x32x16_bf16 v[96:111], v[206:209], v[76:79], v[96:111]
	ds_read_b128 v[206:209], v233 offset:25600
	v_mfma_f32_32x32x16_bf16 v[96:111], v[210:213], v[80:83], v[96:111]
	v_mfma_f32_32x32x16_bf16 v[96:111], v[214:217], v[84:87], v[96:111]
	s_waitcnt lgkmcnt(10)
	v_mfma_f32_32x32x16_bf16 v[96:111], v[144:147], v[88:91], v[96:111]
	ds_read_b64_tr_b16 v[210:211], v244 offset:0
	ds_read_b64_tr_b16 v[212:213], v245 offset:0
	s_waitcnt lgkmcnt(10)
	v_mfma_f32_32x32x16_bf16 v[96:111], v[148:151], v[92:95], v[96:111]
	ds_read_b64_tr_b16 v[214:215], v244 offset:4096
	ds_read_b64_tr_b16 v[216:217], v245 offset:4096
	s_waitcnt lgkmcnt(11)
	v_mfma_f32_32x32x16_bf16 v[112:127], v[152:155], v[64:67], 0
	s_waitcnt lgkmcnt(10)
	v_mfma_f32_32x32x16_bf16 v[112:127], v[156:159], v[68:71], v[112:127]
	ds_read_b64_tr_b16 v[144:145], v244 offset:8192
	ds_read_b64_tr_b16 v[146:147], v245 offset:8192
	s_waitcnt lgkmcnt(11)
	v_mfma_f32_32x32x16_bf16 v[112:127], v[184:187], v[72:75], v[112:127]
	s_waitcnt lgkmcnt(10)
	v_mfma_f32_32x32x16_bf16 v[112:127], v[188:191], v[76:79], v[112:127]
	ds_read_b64_tr_b16 v[148:149], v244 offset:12288
	ds_read_b64_tr_b16 v[150:151], v245 offset:12288
	s_waitcnt lgkmcnt(11)
	v_mfma_f32_32x32x16_bf16 v[112:127], v[192:195], v[80:83], v[112:127]
	ds_read2_b64 v[152:155], v254 offset0:0 offset1:2
	s_waitcnt lgkmcnt(11)
	v_mfma_f32_32x32x16_bf16 v[112:127], v[196:199], v[84:87], v[112:127]
	ds_read2_b64 v[156:159], v254 offset0:4 offset1:6
	s_waitcnt lgkmcnt(11)
	v_mfma_f32_32x32x16_bf16 v[112:127], v[202:205], v[88:91], v[112:127]
	ds_read2_b64 v[184:187], v254 offset0:8 offset1:10
	s_waitcnt lgkmcnt(11)
	v_mfma_f32_32x32x16_bf16 v[112:127], v[206:209], v[92:95], v[112:127]
	ds_read2_b64 v[188:191], v254 offset0:12 offset1:14
	s_waitcnt lgkmcnt(10)
	v_cvt_pk_bf16_f32 v96, v96, v97
	v_cvt_pk_bf16_f32 v97, v98, v99
	v_cvt_pk_bf16_f32 v98, v100, v101
	v_cvt_pk_bf16_f32 v99, v102, v103
	v_cvt_pk_bf16_f32 v100, v104, v105
	v_cvt_pk_bf16_f32 v101, v106, v107
	v_cvt_pk_bf16_f32 v102, v108, v109
	v_cvt_pk_bf16_f32 v103, v110, v111
	s_nop 1
	v_cndmask_b32_e64 v112, v112, 0, s[38:39]
	v_cndmask_b32_e64 v113, v113, 0, s[40:41]
	v_cndmask_b32_e64 v114, v114, 0, s[42:43]
	v_cndmask_b32_e64 v115, v115, 0, s[44:45]
	v_cndmask_b32_e64 v116, v116, 0, s[46:47]
	v_cndmask_b32_e64 v117, v117, 0, s[48:49]
	v_cndmask_b32_e64 v118, v118, 0, s[50:51]
	v_cndmask_b32_e64 v119, v119, 0, s[52:53]
	v_cndmask_b32_e64 v120, v120, 0, s[54:55]
	v_cndmask_b32_e64 v121, v121, 0, s[56:57]
	v_cndmask_b32_e64 v122, v122, 0, s[58:59]
	v_cndmask_b32_e64 v123, v123, 0, s[60:61]
	v_cndmask_b32_e64 v124, v124, 0, s[62:63]
	v_cndmask_b32_e64 v125, v125, 0, s[64:65]
	v_cndmask_b32_e64 v126, v126, 0, s[66:67]
	v_cndmask_b32_e64 v127, v127, 0, s[68:69]
	v_cvt_pk_bf16_f32 v112, v112, v113
	v_cvt_pk_bf16_f32 v113, v114, v115
	v_cvt_pk_bf16_f32 v114, v116, v117
	v_cvt_pk_bf16_f32 v115, v118, v119
	v_cvt_pk_bf16_f32 v116, v120, v121
	v_cvt_pk_bf16_f32 v117, v122, v123
	v_cvt_pk_bf16_f32 v118, v124, v125
	v_cvt_pk_bf16_f32 v119, v126, v127
	ds_read2_b64 v[192:195], v254 offset0:16 offset1:18
	ds_read2_b64 v[196:199], v254 offset0:20 offset1:22
	v_mfma_f32_32x32x16_bf16 v[128:143], v[210:213], v[96:99], 0
	s_waitcnt lgkmcnt(10)
	v_mfma_f32_32x32x16_bf16 v[128:143], v[214:217], v[100:103], v[128:143]
	ds_read2_b64 v[202:205], v254 offset0:24 offset1:26
	ds_read2_b64 v[206:209], v254 offset0:28 offset1:30
	s_waitcnt lgkmcnt(10)
	v_mfma_f32_32x32x16_bf16 v[128:143], v[144:147], v[112:115], v[128:143]
	ds_read_b64_tr_b16 v[210:211], v242 offset:0
	ds_read_b64_tr_b16 v[212:213], v243 offset:0
	s_waitcnt lgkmcnt(10)
	v_mfma_f32_32x32x16_bf16 v[128:143], v[148:151], v[116:119], v[128:143]
	v_cvt_pk_bf16_f32 v218, v0, v1
	v_cvt_pk_bf16_f32 v219, v2, v3
	v_cvt_pk_bf16_f32 v220, v4, v5
	v_cvt_pk_bf16_f32 v221, v6, v7
	ds_read_b64_tr_b16 v[214:215], v234 offset:17408
	ds_read_b64_tr_b16 v[216:217], v235 offset:17408
	s_waitcnt lgkmcnt(11)
	s_nop 1
	v_mfma_f32_32x32x16_bf16 v[128:143], v[218:221], v[152:155], v[128:143]
	v_cvt_pk_bf16_f32 v222, v8, v9
	v_cvt_pk_bf16_f32 v223, v10, v11
	v_cvt_pk_bf16_f32 v224, v12, v13
	v_cvt_pk_bf16_f32 v225, v14, v15
	s_waitcnt lgkmcnt(10)
	s_nop 1
	v_mfma_f32_32x32x16_bf16 v[128:143], v[222:225], v[156:159], v[128:143]
	v_cvt_pk_bf16_f32 v218, v16, v17
	v_cvt_pk_bf16_f32 v219, v18, v19
	v_cvt_pk_bf16_f32 v220, v20, v21
	v_cvt_pk_bf16_f32 v221, v22, v23
	ds_read_b64_tr_b16 v[144:145], v236 offset:17408
	ds_read_b64_tr_b16 v[146:147], v237 offset:17408
	s_waitcnt lgkmcnt(11)
	s_nop 1
	v_mfma_f32_32x32x16_bf16 v[128:143], v[218:221], v[184:187], v[128:143]
	v_cvt_pk_bf16_f32 v222, v24, v25
	v_cvt_pk_bf16_f32 v223, v26, v27
	v_cvt_pk_bf16_f32 v224, v28, v29
	v_cvt_pk_bf16_f32 v225, v30, v31
	s_waitcnt lgkmcnt(10)
	s_nop 1
	v_mfma_f32_32x32x16_bf16 v[128:143], v[222:225], v[188:191], v[128:143]
	v_cvt_pk_bf16_f32 v218, v32, v33
	v_cvt_pk_bf16_f32 v219, v34, v35
	v_cvt_pk_bf16_f32 v220, v36, v37
	v_cvt_pk_bf16_f32 v221, v38, v39
	ds_read_b64_tr_b16 v[148:149], v238 offset:17408
	ds_read_b64_tr_b16 v[150:151], v239 offset:17408
	s_waitcnt lgkmcnt(11)
	s_nop 1
	v_mfma_f32_32x32x16_bf16 v[128:143], v[218:221], v[192:195], v[128:143]
	v_cvt_pk_bf16_f32 v222, v40, v41
	v_cvt_pk_bf16_f32 v223, v42, v43
	v_cvt_pk_bf16_f32 v224, v44, v45
	v_cvt_pk_bf16_f32 v225, v46, v47
	s_waitcnt lgkmcnt(10)
	s_nop 1
	v_mfma_f32_32x32x16_bf16 v[128:143], v[222:225], v[196:199], v[128:143]
	v_cvt_pk_bf16_f32 v218, v48, v49
	v_cvt_pk_bf16_f32 v219, v50, v51
	v_cvt_pk_bf16_f32 v220, v52, v53
	v_cvt_pk_bf16_f32 v221, v54, v55
	ds_read_b64_tr_b16 v[152:153], v240 offset:17408
	ds_read_b64_tr_b16 v[154:155], v241 offset:17408
	s_waitcnt lgkmcnt(11)
	s_nop 1
	v_mfma_f32_32x32x16_bf16 v[128:143], v[218:221], v[202:205], v[128:143]
	v_cvt_pk_bf16_f32 v222, v56, v57
	v_cvt_pk_bf16_f32 v223, v58, v59
	v_cvt_pk_bf16_f32 v224, v60, v61
	v_cvt_pk_bf16_f32 v225, v62, v63
	s_waitcnt lgkmcnt(10)
	s_nop 1
	v_mfma_f32_32x32x16_bf16 v[128:143], v[222:225], v[206:209], v[128:143]
	ds_read_b64_tr_b16 v[156:157], v242 offset:4096
	ds_read_b64_tr_b16 v[158:159], v243 offset:4096
	s_waitcnt lgkmcnt(10)
	s_nop 8
	v_cvt_pk_bf16_f32 v218, v128, v129
	v_cvt_pk_bf16_f32 v219, v130, v131
	v_cvt_pk_bf16_f32 v220, v132, v133
	v_cvt_pk_bf16_f32 v221, v134, v135
	v_cvt_pk_bf16_f32 v222, v136, v137
	v_cvt_pk_bf16_f32 v223, v138, v139
	v_cvt_pk_bf16_f32 v224, v140, v141
	v_cvt_pk_bf16_f32 v225, v142, v143
	ds_write2_b64 v168, v[218:219], v[220:221] offset1:2
	ds_write2_b64 v168, v[222:223], v[224:225] offset0:4 offset1:6
	ds_read_b128 v[218:221], v169
	ds_read_b128 v[222:225], v170
	v_add_u32_e32 v183, s73, v171
	v_add_u32_e32 v201, s75, v171
	s_waitcnt lgkmcnt(0)
	global_store_dwordx4 v183, v[218:221], s[14:15]
	global_store_dwordx4 v201, v[222:225], s[14:15]
	ds_read_b64_tr_b16 v[184:185], v234 offset:21504
	ds_read_b64_tr_b16 v[186:187], v235 offset:21504
	ds_read_b64_tr_b16 v[188:189], v236 offset:21504
	ds_read_b64_tr_b16 v[190:191], v237 offset:21504
	ds_read_b64_tr_b16 v[192:193], v238 offset:21504
	ds_read_b64_tr_b16 v[194:195], v239 offset:21504
	ds_read_b64_tr_b16 v[196:197], v240 offset:21504
	ds_read_b64_tr_b16 v[198:199], v241 offset:21504
	ds_read_b64_tr_b16 v[202:203], v242 offset:8192
	ds_read_b64_tr_b16 v[204:205], v243 offset:8192
	ds_read_b64_tr_b16 v[206:207], v234 offset:25600
	ds_read_b64_tr_b16 v[208:209], v235 offset:25600
	v_mfma_f32_32x32x16_bf16 v[0:15], v[214:217], v[210:213], v[0:15]
	v_mfma_f32_32x32x16_bf16 v[16:31], v[144:147], v[210:213], v[16:31]
	v_mfma_f32_32x32x16_bf16 v[32:47], v[148:151], v[210:213], v[32:47]
	v_mfma_f32_32x32x16_bf16 v[48:63], v[152:155], v[210:213], v[48:63]
	s_waitcnt lgkmcnt(10)
	v_mfma_f32_32x32x16_bf16 v[0:15], v[184:187], v[156:159], v[0:15]
	ds_read_b64_tr_b16 v[214:215], v236 offset:25600
	ds_read_b64_tr_b16 v[216:217], v237 offset:25600
	s_waitcnt lgkmcnt(10)
	v_mfma_f32_32x32x16_bf16 v[16:31], v[188:191], v[156:159], v[16:31]
	ds_read_b64_tr_b16 v[144:145], v238 offset:25600
	ds_read_b64_tr_b16 v[146:147], v239 offset:25600
	s_waitcnt lgkmcnt(10)
	v_mfma_f32_32x32x16_bf16 v[32:47], v[192:195], v[156:159], v[32:47]
	ds_read_b64_tr_b16 v[148:149], v240 offset:25600
	ds_read_b64_tr_b16 v[150:151], v241 offset:25600
	s_waitcnt lgkmcnt(10)
	v_mfma_f32_32x32x16_bf16 v[48:63], v[196:199], v[156:159], v[48:63]
	ds_read_b64_tr_b16 v[152:153], v242 offset:12288
	ds_read_b64_tr_b16 v[154:155], v243 offset:12288
	s_waitcnt lgkmcnt(8)
	v_mfma_f32_32x32x16_bf16 v[0:15], v[206:209], v[202:205], v[0:15]
	ds_read_b64_tr_b16 v[210:211], v234 offset:29696
	ds_read_b64_tr_b16 v[212:213], v235 offset:29696
	ds_read_b64_tr_b16 v[184:185], v236 offset:29696
	ds_read_b64_tr_b16 v[186:187], v237 offset:29696
	s_waitcnt lgkmcnt(10)
	v_mfma_f32_32x32x16_bf16 v[16:31], v[214:217], v[202:205], v[16:31]
	ds_read_b64_tr_b16 v[188:189], v238 offset:29696
	ds_read_b64_tr_b16 v[190:191], v239 offset:29696
	s_waitcnt lgkmcnt(10)
	v_mfma_f32_32x32x16_bf16 v[32:47], v[144:147], v[202:205], v[32:47]
	ds_read_b64_tr_b16 v[192:193], v240 offset:29696
	ds_read_b64_tr_b16 v[194:195], v241 offset:29696
	s_waitcnt lgkmcnt(10)
	v_mfma_f32_32x32x16_bf16 v[48:63], v[148:151], v[202:205], v[48:63]
	ds_read_b128 v[196:199], v255 offset:512
	ds_read_b128 v[156:159], v255 offset:544
	s_waitcnt lgkmcnt(8)
	v_mfma_f32_32x32x16_bf16 v[0:15], v[210:213], v[152:155], v[0:15]
	ds_read_b128 v[206:209], v255 offset:576
	ds_read_b128 v[214:217], v255 offset:608
	ds_read_b128 v[144:147], v255 offset:640
	ds_read_b128 v[148:151], v255 offset:672
	s_waitcnt lgkmcnt(10)
	v_mfma_f32_32x32x16_bf16 v[16:31], v[184:187], v[152:155], v[16:31]
	ds_read_b128 v[202:205], v255 offset:704
	ds_read_b128 v[210:213], v255 offset:736
	s_waitcnt lgkmcnt(10)
	v_mfma_f32_32x32x16_bf16 v[32:47], v[188:191], v[152:155], v[32:47]
	ds_read_b128 v[184:187], v255 offset:768
	ds_read_b128 v[188:191], v255 offset:800
	s_waitcnt lgkmcnt(10)
	v_mfma_f32_32x32x16_bf16 v[48:63], v[192:195], v[152:155], v[48:63]
	ds_read_b128 v[192:195], v255 offset:832
	ds_read_b128 v[152:155], v255 offset:864
	s_waitcnt lgkmcnt(11)
	v_pk_mul_f32 v[0:1], v[0:1], v[196:197]
	v_pk_mul_f32 v[2:3], v[2:3], v[198:199]
	ds_read_b128 v[196:199], v255 offset:896
	s_waitcnt lgkmcnt(11)
	v_pk_mul_f32 v[4:5], v[4:5], v[156:157]
	v_pk_mul_f32 v[6:7], v[6:7], v[158:159]
	ds_read_b128 v[156:159], v255 offset:928
	s_waitcnt lgkmcnt(11)
	v_pk_mul_f32 v[8:9], v[8:9], v[206:207]
	v_pk_mul_f32 v[10:11], v[10:11], v[208:209]
	ds_read_b128 v[206:209], v255 offset:960
	s_waitcnt lgkmcnt(11)
	v_pk_mul_f32 v[12:13], v[12:13], v[214:215]
	v_pk_mul_f32 v[14:15], v[14:15], v[216:217]
	ds_read_b128 v[214:217], v255 offset:992
	s_waitcnt lgkmcnt(11)
	v_pk_mul_f32 v[16:17], v[16:17], v[144:145]
	v_pk_mul_f32 v[18:19], v[18:19], v[146:147]
	s_waitcnt lgkmcnt(10)
	v_pk_mul_f32 v[20:21], v[20:21], v[148:149]
	v_pk_mul_f32 v[22:23], v[22:23], v[150:151]
	s_waitcnt lgkmcnt(9)
	v_pk_mul_f32 v[24:25], v[24:25], v[202:203]
	v_pk_mul_f32 v[26:27], v[26:27], v[204:205]
	s_waitcnt lgkmcnt(8)
	v_pk_mul_f32 v[28:29], v[28:29], v[210:211]
	v_pk_mul_f32 v[30:31], v[30:31], v[212:213]
	s_waitcnt lgkmcnt(7)
	v_pk_mul_f32 v[32:33], v[32:33], v[184:185]
	v_pk_mul_f32 v[34:35], v[34:35], v[186:187]
	s_waitcnt lgkmcnt(6)
	v_pk_mul_f32 v[36:37], v[36:37], v[188:189]
	v_pk_mul_f32 v[38:39], v[38:39], v[190:191]
	s_waitcnt lgkmcnt(5)
	v_pk_mul_f32 v[40:41], v[40:41], v[192:193]
	v_pk_mul_f32 v[42:43], v[42:43], v[194:195]
	s_waitcnt lgkmcnt(4)
	v_pk_mul_f32 v[44:45], v[44:45], v[152:153]
	v_pk_mul_f32 v[46:47], v[46:47], v[154:155]
	s_waitcnt lgkmcnt(3)
	v_pk_mul_f32 v[48:49], v[48:49], v[196:197]
	v_pk_mul_f32 v[50:51], v[50:51], v[198:199]
	s_waitcnt lgkmcnt(2)
	v_pk_mul_f32 v[52:53], v[52:53], v[156:157]
	v_pk_mul_f32 v[54:55], v[54:55], v[158:159]
	s_waitcnt lgkmcnt(1)
	v_pk_mul_f32 v[56:57], v[56:57], v[206:207]
	v_pk_mul_f32 v[58:59], v[58:59], v[208:209]
	s_waitcnt lgkmcnt(0)
	v_pk_mul_f32 v[60:61], v[60:61], v[214:215]
	v_pk_mul_f32 v[62:63], v[62:63], v[216:217]
	v_add_u32_e32 v171, s33, v171
	s_mov_b32 s77, s76
	s_add_u32 s76, s76, 0x4000
	s_cmp_eq_u32 s76, 0x10400
	s_cselect_b32 s76, 0x1b400, s76
	s_cmp_eq_u32 s76, 0x23400
	s_cselect_b32 s76, 0x8400, s76
	s_sub_u32 s77, s76, s77
	v_add_u32_e32 v244, s77, v244
	v_add_u32_e32 v245, s77, v245
	v_add_u32_e32 v242, s77, v242
	v_add_u32_e32 v243, s77, v243
	s_barrier
	s_add_u32 s70, s70, 1
	s_cmp_lt_u32 s70, 32
	s_cbranch_scc1 .Lh2_mfma_loop
	s_branch .Lh2_done
.Lh2_done:
	s_barrier
	s_branch .LBB0_445
.LBB0_445:
	v_readlane_b32 s70, v246, 54
	v_readlane_b32 s50, v246, 48
	v_readlane_b32 s68, v246, 58
	v_readlane_b32 s73, v246, 53
	v_readlane_b32 s71, v246, 55
	v_readlane_b32 s72, v246, 56
	v_readlane_b32 s54, v246, 57
	v_readlane_b32 s51, v246, 49
	v_readlane_b32 s69, v246, 59
	v_readlane_b32 s63, v246, 52
